# combo21 + GEMM MFMA issue order inside each 8-MFMA group changed to a snake (one operand register repeats between consecutive MFMAs); same accumulation order per accumulator
# speedup vs baseline: 1.0025x; 1.0025x over previous
.LBB0_236:
	ds_read_b128 v[154:157], v150
	ds_read_b128 v[158:161], v150 offset:1024
	ds_read_b128 v[162:165], v150 offset:2048
	ds_read_b128 v[166:169], v150 offset:3072
	ds_read_b128 v[172:175], v151
	ds_read_b128 v[176:179], v151 offset:1024
	ds_read_b128 v[180:183], v151 offset:2048
	ds_read_b128 v[184:187], v151 offset:3072
	s_add_u32 s36, s34, 0xfffc0080
	s_addc_u32 s37, s35, -1
	s_cmp_eq_u32 s66, 12
	s_cselect_b32 s39, s21, s37
	s_cselect_b32 s38, s62, s36
	s_cselect_b32 s37, s19, s65
	s_cselect_b32 s36, s63, s64
	v_lshl_add_u64 v[220:221], s[34:35], 0, v[138:139]
	s_add_i32 m0, s27, 0xc000
	ds_read_b128 v[188:191], v152
	ds_read_b128 v[192:195], v152 offset:1024
	ds_read_b128 v[196:199], v152 offset:2048
	ds_read_b128 v[200:203], v152 offset:3072
	ds_read_b128 v[204:207], v152 offset:4096
	ds_read_b128 v[208:211], v152 offset:5120
	ds_read_b128 v[212:215], v152 offset:6144
	ds_read_b128 v[216:219], v152 offset:7168
	global_load_lds_dwordx4 v[220:221], off
	v_lshl_add_u64 v[220:221], s[34:35], 0, v[140:141]
	s_add_i32 m0, s27, 0xe000
	s_nop 0
	global_load_lds_dwordx4 v[220:221], off
	s_waitcnt vmcnt(8)
	s_waitcnt lgkmcnt(0)
	s_barrier
	s_setprio 1
	s_waitcnt lgkmcnt(0)
	v_mfma_f32_16x16x32_bf16 v[124:127], v[154:157], v[188:191], v[124:127]
	v_mfma_f32_16x16x32_bf16 v[116:119], v[154:157], v[196:199], v[116:119]
	v_mfma_f32_16x16x32_bf16 v[108:111], v[154:157], v[204:207], v[108:111]
	v_mfma_f32_16x16x32_bf16 v[76:79], v[154:157], v[212:215], v[76:79]
	v_mfma_f32_16x16x32_bf16 v[72:75], v[162:165], v[212:215], v[72:75]
	v_mfma_f32_16x16x32_bf16 v[100:103], v[162:165], v[204:207], v[100:103]
	v_mfma_f32_16x16x32_bf16 v[112:115], v[162:165], v[196:199], v[112:115]
	v_mfma_f32_16x16x32_bf16 v[120:123], v[162:165], v[188:191], v[120:123]
	v_mfma_f32_16x16x32_bf16 v[124:127], v[158:161], v[192:195], v[124:127]
	v_mfma_f32_16x16x32_bf16 v[116:119], v[158:161], v[200:203], v[116:119]
	v_mfma_f32_16x16x32_bf16 v[108:111], v[158:161], v[208:211], v[108:111]
	v_mfma_f32_16x16x32_bf16 v[76:79], v[158:161], v[216:219], v[76:79]
	v_mfma_f32_16x16x32_bf16 v[72:75], v[166:169], v[216:219], v[72:75]
	v_mfma_f32_16x16x32_bf16 v[100:103], v[166:169], v[208:211], v[100:103]
	v_mfma_f32_16x16x32_bf16 v[112:115], v[166:169], v[200:203], v[112:115]
	v_mfma_f32_16x16x32_bf16 v[120:123], v[166:169], v[192:195], v[120:123]
	s_setprio 0
	s_setprio 1
	v_mfma_f32_16x16x32_bf16 v[104:107], v[172:175], v[188:191], v[104:107]
	v_mfma_f32_16x16x32_bf16 v[92:95], v[172:175], v[196:199], v[92:95]
	v_mfma_f32_16x16x32_bf16 v[84:87], v[172:175], v[204:207], v[84:87]
	v_mfma_f32_16x16x32_bf16 v[68:71], v[172:175], v[212:215], v[68:71]
	v_mfma_f32_16x16x32_bf16 v[64:67], v[180:183], v[212:215], v[64:67]
	v_mfma_f32_16x16x32_bf16 v[80:83], v[180:183], v[204:207], v[80:83]
	v_mfma_f32_16x16x32_bf16 v[88:91], v[180:183], v[196:199], v[88:91]
	v_mfma_f32_16x16x32_bf16 v[96:99], v[180:183], v[188:191], v[96:99]
	v_mfma_f32_16x16x32_bf16 v[104:107], v[176:179], v[192:195], v[104:107]
	v_mfma_f32_16x16x32_bf16 v[92:95], v[176:179], v[200:203], v[92:95]
	v_mfma_f32_16x16x32_bf16 v[84:87], v[176:179], v[208:211], v[84:87]
	v_mfma_f32_16x16x32_bf16 v[68:71], v[176:179], v[216:219], v[68:71]
	v_mfma_f32_16x16x32_bf16 v[64:67], v[184:187], v[216:219], v[64:67]
	v_mfma_f32_16x16x32_bf16 v[80:83], v[184:187], v[208:211], v[80:83]
	v_mfma_f32_16x16x32_bf16 v[88:91], v[184:187], v[200:203], v[88:91]
	v_mfma_f32_16x16x32_bf16 v[96:99], v[184:187], v[192:195], v[96:99]
	s_setprio 0
	s_barrier
	s_add_i32 s67, s54, s43
	v_lshl_add_u64 v[220:221], s[36:37], 0, v[132:133]
	s_mov_b32 m0, s67
	ds_read_b128 v[188:191], v152 offset:16384
	ds_read_b128 v[192:195], v152 offset:17408
	ds_read_b128 v[196:199], v152 offset:18432
	ds_read_b128 v[200:203], v152 offset:19456
	ds_read_b128 v[204:207], v152 offset:20480
	ds_read_b128 v[208:211], v152 offset:21504
	ds_read_b128 v[212:215], v152 offset:22528
	ds_read_b128 v[216:219], v152 offset:23552
	global_load_lds_dwordx4 v[220:221], off
	s_add_i32 m0, s67, 0x2000
	s_add_u32 s68, s36, 0x40000
	v_lshl_add_u64 v[222:223], s[36:37], 0, v[128:129]
	s_addc_u32 s69, s37, 0
	s_add_i32 s67, s55, s43
	global_load_lds_dwordx4 v[222:223], off
	v_lshl_add_u64 v[224:225], s[68:69], 0, v[132:133]
	s_mov_b32 m0, s67
	v_lshl_add_u64 v[226:227], s[38:39], 0, v[130:131]
	global_load_lds_dwordx4 v[224:225], off
	v_lshl_add_u64 v[224:225], s[68:69], 0, v[128:129]
	s_add_i32 m0, s67, 0x2000
	s_nop 0
	global_load_lds_dwordx4 v[224:225], off
	v_lshl_add_u64 v[224:225], s[38:39], 0, v[134:135]
	s_mov_b32 m0, s27
	s_nop 0
	global_load_lds_dwordx4 v[224:225], off
	s_mov_b32 m0, s46
	s_nop 0
	global_load_lds_dwordx4 v[226:227], off
	s_waitcnt vmcnt(8)
	s_waitcnt lgkmcnt(0)
	s_barrier
	s_setprio 1
	s_waitcnt lgkmcnt(0)
	v_mfma_f32_16x16x32_bf16 v[60:63], v[154:157], v[188:191], v[60:63]
	v_mfma_f32_16x16x32_bf16 v[52:55], v[154:157], v[196:199], v[52:55]
	v_mfma_f32_16x16x32_bf16 v[36:39], v[154:157], v[204:207], v[36:39]
	v_mfma_f32_16x16x32_bf16 v[20:23], v[154:157], v[212:215], v[20:23]
	v_mfma_f32_16x16x32_bf16 v[12:15], v[162:165], v[212:215], v[12:15]
	v_mfma_f32_16x16x32_bf16 v[28:31], v[162:165], v[204:207], v[28:31]
	v_mfma_f32_16x16x32_bf16 v[44:47], v[162:165], v[196:199], v[44:47]
	v_mfma_f32_16x16x32_bf16 v[56:59], v[162:165], v[188:191], v[56:59]
	v_mfma_f32_16x16x32_bf16 v[60:63], v[158:161], v[192:195], v[60:63]
	v_mfma_f32_16x16x32_bf16 v[52:55], v[158:161], v[200:203], v[52:55]
	v_mfma_f32_16x16x32_bf16 v[36:39], v[158:161], v[208:211], v[36:39]
	v_mfma_f32_16x16x32_bf16 v[20:23], v[158:161], v[216:219], v[20:23]
	v_mfma_f32_16x16x32_bf16 v[12:15], v[166:169], v[216:219], v[12:15]
	v_mfma_f32_16x16x32_bf16 v[28:31], v[166:169], v[208:211], v[28:31]
	v_mfma_f32_16x16x32_bf16 v[44:47], v[166:169], v[200:203], v[44:47]
	v_mfma_f32_16x16x32_bf16 v[56:59], v[166:169], v[192:195], v[56:59]
	s_setprio 0
	s_setprio 1
	v_mfma_f32_16x16x32_bf16 v[48:51], v[172:175], v[188:191], v[48:51]
	v_mfma_f32_16x16x32_bf16 v[32:35], v[172:175], v[196:199], v[32:35]
	v_mfma_f32_16x16x32_bf16 v[16:19], v[172:175], v[204:207], v[16:19]
	v_mfma_f32_16x16x32_bf16 v[4:7], v[172:175], v[212:215], v[4:7]
	v_mfma_f32_16x16x32_bf16 v[0:3], v[180:183], v[212:215], v[0:3]
	v_mfma_f32_16x16x32_bf16 v[8:11], v[180:183], v[204:207], v[8:11]
	v_mfma_f32_16x16x32_bf16 v[24:27], v[180:183], v[196:199], v[24:27]
	v_mfma_f32_16x16x32_bf16 v[40:43], v[180:183], v[188:191], v[40:43]
	v_mfma_f32_16x16x32_bf16 v[48:51], v[176:179], v[192:195], v[48:51]
	v_mfma_f32_16x16x32_bf16 v[32:35], v[176:179], v[200:203], v[32:35]
	v_mfma_f32_16x16x32_bf16 v[16:19], v[176:179], v[208:211], v[16:19]
	v_mfma_f32_16x16x32_bf16 v[4:7], v[176:179], v[216:219], v[4:7]
	v_mfma_f32_16x16x32_bf16 v[0:3], v[184:187], v[216:219], v[0:3]
	v_mfma_f32_16x16x32_bf16 v[8:11], v[184:187], v[208:211], v[8:11]
	v_mfma_f32_16x16x32_bf16 v[24:27], v[184:187], v[200:203], v[24:27]
	v_mfma_f32_16x16x32_bf16 v[40:43], v[184:187], v[192:195], v[40:43]
	s_setprio 0
	s_barrier
	s_cmp_lg_u32 s66, 12
	s_cbranch_scc1 .Lmy_rs0_skip
	v_lshl_add_u32 v230, s26, 8, v147
	v_ashrrev_i32_e32 v231, 31, v230
	v_lshl_add_u64 v[232:233], v[230:231], 2, s[6:7]
	global_load_dword v230, v[232:233], off
	global_load_dword v234, v[232:233], off offset:128
	global_load_dword v236, v[232:233], off offset:192
	global_load_dword v238, v[232:233], off offset:512
	global_load_dword v240, v[232:233], off offset:576
	global_load_dword v242, v[232:233], off offset:640
	global_load_dword v244, v[232:233], off offset:704
	global_load_dword v232, v[232:233], off offset:64

.Lmy_rs0_wd:
	s_waitcnt lgkmcnt(0)
	s_barrier
	s_setprio 1
	s_waitcnt lgkmcnt(0)
	v_mfma_f32_16x16x32_bf16 v[124:127], v[154:157], v[188:191], v[124:127]
	v_mfma_f32_16x16x32_bf16 v[116:119], v[154:157], v[196:199], v[116:119]
	v_mfma_f32_16x16x32_bf16 v[108:111], v[154:157], v[204:207], v[108:111]
	v_mfma_f32_16x16x32_bf16 v[76:79], v[154:157], v[212:215], v[76:79]
	v_mfma_f32_16x16x32_bf16 v[72:75], v[162:165], v[212:215], v[72:75]
	v_mfma_f32_16x16x32_bf16 v[100:103], v[162:165], v[204:207], v[100:103]
	v_mfma_f32_16x16x32_bf16 v[112:115], v[162:165], v[196:199], v[112:115]
	v_mfma_f32_16x16x32_bf16 v[120:123], v[162:165], v[188:191], v[120:123]
	v_mfma_f32_16x16x32_bf16 v[124:127], v[158:161], v[192:195], v[124:127]
	v_mfma_f32_16x16x32_bf16 v[116:119], v[158:161], v[200:203], v[116:119]
	v_mfma_f32_16x16x32_bf16 v[108:111], v[158:161], v[208:211], v[108:111]
	v_mfma_f32_16x16x32_bf16 v[76:79], v[158:161], v[216:219], v[76:79]
	v_mfma_f32_16x16x32_bf16 v[72:75], v[166:169], v[216:219], v[72:75]
	v_mfma_f32_16x16x32_bf16 v[100:103], v[166:169], v[208:211], v[100:103]
	v_mfma_f32_16x16x32_bf16 v[112:115], v[166:169], v[200:203], v[112:115]
	v_mfma_f32_16x16x32_bf16 v[120:123], v[166:169], v[192:195], v[120:123]
	s_setprio 0
	s_setprio 1
	v_mfma_f32_16x16x32_bf16 v[104:107], v[172:175], v[188:191], v[104:107]
	v_mfma_f32_16x16x32_bf16 v[92:95], v[172:175], v[196:199], v[92:95]
	v_mfma_f32_16x16x32_bf16 v[84:87], v[172:175], v[204:207], v[84:87]
	v_mfma_f32_16x16x32_bf16 v[68:71], v[172:175], v[212:215], v[68:71]
	v_mfma_f32_16x16x32_bf16 v[64:67], v[180:183], v[212:215], v[64:67]
	v_mfma_f32_16x16x32_bf16 v[80:83], v[180:183], v[204:207], v[80:83]
	v_mfma_f32_16x16x32_bf16 v[88:91], v[180:183], v[196:199], v[88:91]
	v_mfma_f32_16x16x32_bf16 v[96:99], v[180:183], v[188:191], v[96:99]
	v_mfma_f32_16x16x32_bf16 v[104:107], v[176:179], v[192:195], v[104:107]
	v_mfma_f32_16x16x32_bf16 v[92:95], v[176:179], v[200:203], v[92:95]
	v_mfma_f32_16x16x32_bf16 v[84:87], v[176:179], v[208:211], v[84:87]
	v_mfma_f32_16x16x32_bf16 v[68:71], v[176:179], v[216:219], v[68:71]
	v_mfma_f32_16x16x32_bf16 v[64:67], v[184:187], v[216:219], v[64:67]
	v_mfma_f32_16x16x32_bf16 v[80:83], v[184:187], v[208:211], v[80:83]
	v_mfma_f32_16x16x32_bf16 v[88:91], v[184:187], v[200:203], v[88:91]
	v_mfma_f32_16x16x32_bf16 v[96:99], v[184:187], v[192:195], v[96:99]
	s_setprio 0
	s_barrier
	s_add_i32 s38, s67, s43
	v_lshl_add_u64 v[220:221], v[220:221], 0, s[8:9]
	s_mov_b32 m0, s38
	ds_read_b128 v[188:191], v152 offset:49152
	ds_read_b128 v[192:195], v152 offset:50176
	ds_read_b128 v[196:199], v152 offset:51200
	ds_read_b128 v[200:203], v152 offset:52224
	ds_read_b128 v[204:207], v152 offset:53248
	ds_read_b128 v[208:211], v152 offset:54272
	ds_read_b128 v[212:215], v152 offset:55296
	ds_read_b128 v[216:219], v152 offset:56320
	global_load_lds_dwordx4 v[220:221], off
	s_add_i32 m0, s38, 0x2000
	s_add_u32 s36, s36, 0x40080
	v_lshl_add_u64 v[220:221], v[222:223], 0, s[8:9]
	s_addc_u32 s37, s37, 0
	s_add_i32 s38, s68, s43
	global_load_lds_dwordx4 v[220:221], off
	v_lshl_add_u64 v[220:221], s[36:37], 0, v[132:133]
	s_mov_b32 m0, s38
	s_nop 0
	global_load_lds_dwordx4 v[220:221], off
	v_lshl_add_u64 v[220:221], s[36:37], 0, v[128:129]
	s_add_i32 m0, s38, 0x2000
	s_nop 0
	global_load_lds_dwordx4 v[220:221], off
	v_lshl_add_u64 v[220:221], v[224:225], 0, s[8:9]
	s_mov_b32 m0, s50
	s_nop 0
	global_load_lds_dwordx4 v[220:221], off
	v_lshl_add_u64 v[220:221], v[226:227], 0, s[8:9]
	s_mov_b32 m0, s51
	s_nop 0
	global_load_lds_dwordx4 v[220:221], off
	s_waitcnt vmcnt(8)
	s_waitcnt lgkmcnt(0)
	s_barrier
	s_setprio 1
	s_waitcnt lgkmcnt(0)
	v_mfma_f32_16x16x32_bf16 v[60:63], v[154:157], v[188:191], v[60:63]
	v_mfma_f32_16x16x32_bf16 v[52:55], v[154:157], v[196:199], v[52:55]
	v_mfma_f32_16x16x32_bf16 v[36:39], v[154:157], v[204:207], v[36:39]
	v_mfma_f32_16x16x32_bf16 v[20:23], v[154:157], v[212:215], v[20:23]
	v_mfma_f32_16x16x32_bf16 v[12:15], v[162:165], v[212:215], v[12:15]
	v_mfma_f32_16x16x32_bf16 v[28:31], v[162:165], v[204:207], v[28:31]
	v_mfma_f32_16x16x32_bf16 v[44:47], v[162:165], v[196:199], v[44:47]
	v_mfma_f32_16x16x32_bf16 v[56:59], v[162:165], v[188:191], v[56:59]
	v_mfma_f32_16x16x32_bf16 v[60:63], v[158:161], v[192:195], v[60:63]
	v_mfma_f32_16x16x32_bf16 v[52:55], v[158:161], v[200:203], v[52:55]
	v_mfma_f32_16x16x32_bf16 v[36:39], v[158:161], v[208:211], v[36:39]
	v_mfma_f32_16x16x32_bf16 v[20:23], v[158:161], v[216:219], v[20:23]
	v_mfma_f32_16x16x32_bf16 v[12:15], v[166:169], v[216:219], v[12:15]
	v_mfma_f32_16x16x32_bf16 v[28:31], v[166:169], v[208:211], v[28:31]
	v_mfma_f32_16x16x32_bf16 v[44:47], v[166:169], v[200:203], v[44:47]
	v_mfma_f32_16x16x32_bf16 v[56:59], v[166:169], v[192:195], v[56:59]
	s_setprio 0
	s_setprio 1
	v_mfma_f32_16x16x32_bf16 v[48:51], v[172:175], v[188:191], v[48:51]
	v_mfma_f32_16x16x32_bf16 v[32:35], v[172:175], v[196:199], v[32:35]
	v_mfma_f32_16x16x32_bf16 v[16:19], v[172:175], v[204:207], v[16:19]
	v_mfma_f32_16x16x32_bf16 v[4:7], v[172:175], v[212:215], v[4:7]
	v_mfma_f32_16x16x32_bf16 v[0:3], v[180:183], v[212:215], v[0:3]
	v_mfma_f32_16x16x32_bf16 v[8:11], v[180:183], v[204:207], v[8:11]
	v_mfma_f32_16x16x32_bf16 v[24:27], v[180:183], v[196:199], v[24:27]
	v_mfma_f32_16x16x32_bf16 v[40:43], v[180:183], v[188:191], v[40:43]
	v_mfma_f32_16x16x32_bf16 v[48:51], v[176:179], v[192:195], v[48:51]
	v_mfma_f32_16x16x32_bf16 v[32:35], v[176:179], v[200:203], v[32:35]
	v_mfma_f32_16x16x32_bf16 v[16:19], v[176:179], v[208:211], v[16:19]
	v_mfma_f32_16x16x32_bf16 v[4:7], v[176:179], v[216:219], v[4:7]
	v_mfma_f32_16x16x32_bf16 v[0:3], v[184:187], v[216:219], v[0:3]
	v_mfma_f32_16x16x32_bf16 v[8:11], v[184:187], v[208:211], v[8:11]
	v_mfma_f32_16x16x32_bf16 v[24:27], v[184:187], v[200:203], v[24:27]
	v_mfma_f32_16x16x32_bf16 v[40:43], v[184:187], v[192:195], v[40:43]
	s_setprio 0
	s_barrier
	s_add_i32 s66, s66, 2
	s_add_u32 s34, s34, 0x100
	s_addc_u32 s35, s35, 0
	s_add_u32 s64, s64, 0x100
	s_addc_u32 s65, s65, 0
	s_cmp_gt_u32 s66, 13
	s_cbranch_scc0 .LBB0_236
	s_and_b64 vcc, exec, s[10:11]
	s_cbranch_vccz .LBB0_239
	s_barrier

.LBB0_445:
	ds_read_b128 v[146:149], v167
	ds_read_b128 v[150:153], v167 offset:1024
	ds_read_b128 v[154:157], v167 offset:2048
	ds_read_b128 v[158:161], v167 offset:3072
	ds_read_b128 v[172:175], v168
	ds_read_b128 v[176:179], v168 offset:1024
	ds_read_b128 v[180:183], v168 offset:2048
	ds_read_b128 v[184:187], v168 offset:3072
	s_add_u32 s48, s46, 0xfffc0080
	s_addc_u32 s49, s47, -1
	s_cmp_eq_u32 s73, 12
	s_cselect_b32 s51, s1, s49
	s_cselect_b32 s50, s39, s48
	s_cselect_b32 s49, s37, s72
	s_cselect_b32 s48, s52, s53
	v_lshl_add_u64 v[162:163], s[46:47], 0, v[138:139]
	s_add_i32 m0, s45, 0xc000
	ds_read_b128 v[188:191], v169
	ds_read_b128 v[192:195], v169 offset:1024
	ds_read_b128 v[196:199], v169 offset:2048
	ds_read_b128 v[200:203], v169 offset:3072
	ds_read_b128 v[204:207], v169 offset:4096
	ds_read_b128 v[208:211], v169 offset:5120
	ds_read_b128 v[212:215], v169 offset:6144
	ds_read_b128 v[216:219], v169 offset:7168
	global_load_lds_dwordx4 v[162:163], off
	v_lshl_add_u64 v[162:163], s[46:47], 0, v[140:141]
	s_add_i32 m0, s45, 0xe000
	s_nop 0
	global_load_lds_dwordx4 v[162:163], off
	s_waitcnt vmcnt(8)
	s_waitcnt lgkmcnt(0)
	s_barrier
	s_setprio 1
	s_waitcnt lgkmcnt(0)
	v_mfma_f32_16x16x32_bf16 v[124:127], v[146:149], v[188:191], v[124:127]
	v_mfma_f32_16x16x32_bf16 v[108:111], v[146:149], v[196:199], v[108:111]
	v_mfma_f32_16x16x32_bf16 v[92:95], v[146:149], v[204:207], v[92:95]
	v_mfma_f32_16x16x32_bf16 v[76:79], v[146:149], v[212:215], v[76:79]
	v_mfma_f32_16x16x32_bf16 v[72:75], v[154:157], v[212:215], v[72:75]
	v_mfma_f32_16x16x32_bf16 v[88:91], v[154:157], v[204:207], v[88:91]
	v_mfma_f32_16x16x32_bf16 v[104:107], v[154:157], v[196:199], v[104:107]
	v_mfma_f32_16x16x32_bf16 v[120:123], v[154:157], v[188:191], v[120:123]
	v_mfma_f32_16x16x32_bf16 v[124:127], v[150:153], v[192:195], v[124:127]
	v_mfma_f32_16x16x32_bf16 v[108:111], v[150:153], v[200:203], v[108:111]
	v_mfma_f32_16x16x32_bf16 v[92:95], v[150:153], v[208:211], v[92:95]
	v_mfma_f32_16x16x32_bf16 v[76:79], v[150:153], v[216:219], v[76:79]
	v_mfma_f32_16x16x32_bf16 v[72:75], v[158:161], v[216:219], v[72:75]
	v_mfma_f32_16x16x32_bf16 v[88:91], v[158:161], v[208:211], v[88:91]
	v_mfma_f32_16x16x32_bf16 v[104:107], v[158:161], v[200:203], v[104:107]
	v_mfma_f32_16x16x32_bf16 v[120:123], v[158:161], v[192:195], v[120:123]
	s_setprio 0
	s_setprio 1
	v_mfma_f32_16x16x32_bf16 v[116:119], v[172:175], v[188:191], v[116:119]
	v_mfma_f32_16x16x32_bf16 v[100:103], v[172:175], v[196:199], v[100:103]
	v_mfma_f32_16x16x32_bf16 v[84:87], v[172:175], v[204:207], v[84:87]
	v_mfma_f32_16x16x32_bf16 v[68:71], v[172:175], v[212:215], v[68:71]
	v_mfma_f32_16x16x32_bf16 v[64:67], v[180:183], v[212:215], v[64:67]
	v_mfma_f32_16x16x32_bf16 v[80:83], v[180:183], v[204:207], v[80:83]
	v_mfma_f32_16x16x32_bf16 v[96:99], v[180:183], v[196:199], v[96:99]
	v_mfma_f32_16x16x32_bf16 v[112:115], v[180:183], v[188:191], v[112:115]
	v_mfma_f32_16x16x32_bf16 v[116:119], v[176:179], v[192:195], v[116:119]
	v_mfma_f32_16x16x32_bf16 v[100:103], v[176:179], v[200:203], v[100:103]
	v_mfma_f32_16x16x32_bf16 v[84:87], v[176:179], v[208:211], v[84:87]
	v_mfma_f32_16x16x32_bf16 v[68:71], v[176:179], v[216:219], v[68:71]
	v_mfma_f32_16x16x32_bf16 v[64:67], v[184:187], v[216:219], v[64:67]
	v_mfma_f32_16x16x32_bf16 v[80:83], v[184:187], v[208:211], v[80:83]
	v_mfma_f32_16x16x32_bf16 v[96:99], v[184:187], v[200:203], v[96:99]
	v_mfma_f32_16x16x32_bf16 v[112:115], v[184:187], v[192:195], v[112:115]
	s_setprio 0
	s_barrier
	s_add_i32 s74, s66, s57
	v_lshl_add_u64 v[162:163], s[48:49], 0, v[130:131]
	s_mov_b32 m0, s74
	ds_read_b128 v[188:191], v169 offset:16384
	ds_read_b128 v[192:195], v169 offset:17408
	ds_read_b128 v[196:199], v169 offset:18432
	ds_read_b128 v[200:203], v169 offset:19456
	ds_read_b128 v[204:207], v169 offset:20480
	ds_read_b128 v[208:211], v169 offset:21504
	ds_read_b128 v[212:215], v169 offset:22528
	ds_read_b128 v[216:219], v169 offset:23552
	global_load_lds_dwordx4 v[162:163], off
	s_add_i32 m0, s74, 0x2000
	s_add_u32 s74, s48, 0x40000
	v_lshl_add_u64 v[220:221], s[48:49], 0, v[134:135]
	s_addc_u32 s75, s49, 0
	s_add_i32 s76, s67, s57
	global_load_lds_dwordx4 v[220:221], off
	v_lshl_add_u64 v[222:223], s[74:75], 0, v[130:131]
	s_mov_b32 m0, s76
	v_lshl_add_u64 v[224:225], s[50:51], 0, v[132:133]
	global_load_lds_dwordx4 v[222:223], off
	v_lshl_add_u64 v[222:223], s[74:75], 0, v[134:135]
	s_add_i32 m0, s76, 0x2000
	s_nop 0
	global_load_lds_dwordx4 v[222:223], off
	v_lshl_add_u64 v[222:223], s[50:51], 0, v[128:129]
	s_mov_b32 m0, s45
	s_nop 0
	global_load_lds_dwordx4 v[222:223], off
	s_mov_b32 m0, s58
	s_nop 0
	global_load_lds_dwordx4 v[224:225], off
	s_waitcnt vmcnt(8)
	s_waitcnt lgkmcnt(0)
	s_barrier
	s_setprio 1
	s_waitcnt lgkmcnt(0)
	v_mfma_f32_16x16x32_bf16 v[60:63], v[146:149], v[188:191], v[60:63]
	v_mfma_f32_16x16x32_bf16 v[44:47], v[146:149], v[196:199], v[44:47]
	v_mfma_f32_16x16x32_bf16 v[28:31], v[146:149], v[204:207], v[28:31]
	v_mfma_f32_16x16x32_bf16 v[12:15], v[146:149], v[212:215], v[12:15]
	v_mfma_f32_16x16x32_bf16 v[8:11], v[154:157], v[212:215], v[8:11]
	v_mfma_f32_16x16x32_bf16 v[24:27], v[154:157], v[204:207], v[24:27]
	v_mfma_f32_16x16x32_bf16 v[40:43], v[154:157], v[196:199], v[40:43]
	v_mfma_f32_16x16x32_bf16 v[56:59], v[154:157], v[188:191], v[56:59]
	v_mfma_f32_16x16x32_bf16 v[60:63], v[150:153], v[192:195], v[60:63]
	v_mfma_f32_16x16x32_bf16 v[44:47], v[150:153], v[200:203], v[44:47]
	v_mfma_f32_16x16x32_bf16 v[28:31], v[150:153], v[208:211], v[28:31]
	v_mfma_f32_16x16x32_bf16 v[12:15], v[150:153], v[216:219], v[12:15]
	v_mfma_f32_16x16x32_bf16 v[8:11], v[158:161], v[216:219], v[8:11]
	v_mfma_f32_16x16x32_bf16 v[24:27], v[158:161], v[208:211], v[24:27]
	v_mfma_f32_16x16x32_bf16 v[40:43], v[158:161], v[200:203], v[40:43]
	v_mfma_f32_16x16x32_bf16 v[56:59], v[158:161], v[192:195], v[56:59]
	s_setprio 0
	s_setprio 1
	v_mfma_f32_16x16x32_bf16 v[52:55], v[172:175], v[188:191], v[52:55]
	v_mfma_f32_16x16x32_bf16 v[36:39], v[172:175], v[196:199], v[36:39]
	v_mfma_f32_16x16x32_bf16 v[20:23], v[172:175], v[204:207], v[20:23]
	v_mfma_f32_16x16x32_bf16 v[4:7], v[172:175], v[212:215], v[4:7]
	v_mfma_f32_16x16x32_bf16 v[0:3], v[180:183], v[212:215], v[0:3]
	v_mfma_f32_16x16x32_bf16 v[16:19], v[180:183], v[204:207], v[16:19]
	v_mfma_f32_16x16x32_bf16 v[32:35], v[180:183], v[196:199], v[32:35]
	v_mfma_f32_16x16x32_bf16 v[48:51], v[180:183], v[188:191], v[48:51]
	v_mfma_f32_16x16x32_bf16 v[52:55], v[176:179], v[192:195], v[52:55]
	v_mfma_f32_16x16x32_bf16 v[36:39], v[176:179], v[200:203], v[36:39]
	v_mfma_f32_16x16x32_bf16 v[20:23], v[176:179], v[208:211], v[20:23]
	v_mfma_f32_16x16x32_bf16 v[4:7], v[176:179], v[216:219], v[4:7]
	v_mfma_f32_16x16x32_bf16 v[0:3], v[184:187], v[216:219], v[0:3]
	v_mfma_f32_16x16x32_bf16 v[16:19], v[184:187], v[208:211], v[16:19]
	v_mfma_f32_16x16x32_bf16 v[32:35], v[184:187], v[200:203], v[32:35]
	v_mfma_f32_16x16x32_bf16 v[48:51], v[184:187], v[192:195], v[48:51]
	s_setprio 0
	s_barrier
	s_cmp_lg_u32 s73, 12
	s_cbranch_scc1 .Lmy_rs5_skip
	v_lshl_add_u32 v230, s0, 8, v164
	v_ashrrev_i32_e32 v231, 31, v230
	v_lshl_add_u64 v[232:233], v[230:231], 2, s[16:17]
	global_load_dword v230, v[232:233], off
	global_load_dword v234, v[232:233], off offset:128
	global_load_dword v236, v[232:233], off offset:192
	global_load_dword v238, v[232:233], off offset:512
	global_load_dword v240, v[232:233], off offset:576
	global_load_dword v242, v[232:233], off offset:640
	global_load_dword v244, v[232:233], off offset:704
	global_load_dword v232, v[232:233], off offset:64

.Lmy_rs5_wd:
	s_waitcnt lgkmcnt(0)
	s_barrier
	s_setprio 1
	s_waitcnt lgkmcnt(0)
	v_mfma_f32_16x16x32_bf16 v[124:127], v[146:149], v[188:191], v[124:127]
	v_mfma_f32_16x16x32_bf16 v[108:111], v[146:149], v[196:199], v[108:111]
	v_mfma_f32_16x16x32_bf16 v[92:95], v[146:149], v[204:207], v[92:95]
	v_mfma_f32_16x16x32_bf16 v[76:79], v[146:149], v[212:215], v[76:79]
	v_mfma_f32_16x16x32_bf16 v[72:75], v[154:157], v[212:215], v[72:75]
	v_mfma_f32_16x16x32_bf16 v[88:91], v[154:157], v[204:207], v[88:91]
	v_mfma_f32_16x16x32_bf16 v[104:107], v[154:157], v[196:199], v[104:107]
	v_mfma_f32_16x16x32_bf16 v[120:123], v[154:157], v[188:191], v[120:123]
	v_mfma_f32_16x16x32_bf16 v[124:127], v[150:153], v[192:195], v[124:127]
	v_mfma_f32_16x16x32_bf16 v[108:111], v[150:153], v[200:203], v[108:111]
	v_mfma_f32_16x16x32_bf16 v[92:95], v[150:153], v[208:211], v[92:95]
	v_mfma_f32_16x16x32_bf16 v[76:79], v[150:153], v[216:219], v[76:79]
	v_mfma_f32_16x16x32_bf16 v[72:75], v[158:161], v[216:219], v[72:75]
	v_mfma_f32_16x16x32_bf16 v[88:91], v[158:161], v[208:211], v[88:91]
	v_mfma_f32_16x16x32_bf16 v[104:107], v[158:161], v[200:203], v[104:107]
	v_mfma_f32_16x16x32_bf16 v[120:123], v[158:161], v[192:195], v[120:123]
	s_setprio 0
	s_setprio 1
	v_mfma_f32_16x16x32_bf16 v[116:119], v[172:175], v[188:191], v[116:119]
	v_mfma_f32_16x16x32_bf16 v[100:103], v[172:175], v[196:199], v[100:103]
	v_mfma_f32_16x16x32_bf16 v[84:87], v[172:175], v[204:207], v[84:87]
	v_mfma_f32_16x16x32_bf16 v[68:71], v[172:175], v[212:215], v[68:71]
	v_mfma_f32_16x16x32_bf16 v[64:67], v[180:183], v[212:215], v[64:67]
	v_mfma_f32_16x16x32_bf16 v[80:83], v[180:183], v[204:207], v[80:83]
	v_mfma_f32_16x16x32_bf16 v[96:99], v[180:183], v[196:199], v[96:99]
	v_mfma_f32_16x16x32_bf16 v[112:115], v[180:183], v[188:191], v[112:115]
	v_mfma_f32_16x16x32_bf16 v[116:119], v[176:179], v[192:195], v[116:119]
	v_mfma_f32_16x16x32_bf16 v[100:103], v[176:179], v[200:203], v[100:103]
	v_mfma_f32_16x16x32_bf16 v[84:87], v[176:179], v[208:211], v[84:87]
	v_mfma_f32_16x16x32_bf16 v[68:71], v[176:179], v[216:219], v[68:71]
	v_mfma_f32_16x16x32_bf16 v[64:67], v[184:187], v[216:219], v[64:67]
	v_mfma_f32_16x16x32_bf16 v[80:83], v[184:187], v[208:211], v[80:83]
	v_mfma_f32_16x16x32_bf16 v[96:99], v[184:187], v[200:203], v[96:99]
	v_mfma_f32_16x16x32_bf16 v[112:115], v[184:187], v[192:195], v[112:115]
	s_setprio 0
	s_barrier
	s_add_i32 s50, s74, s57
	v_lshl_add_u64 v[162:163], v[162:163], 0, s[18:19]
	s_mov_b32 m0, s50
	ds_read_b128 v[188:191], v169 offset:49152
	ds_read_b128 v[192:195], v169 offset:50176
	ds_read_b128 v[196:199], v169 offset:51200
	ds_read_b128 v[200:203], v169 offset:52224
	ds_read_b128 v[204:207], v169 offset:53248
	ds_read_b128 v[208:211], v169 offset:54272
	ds_read_b128 v[212:215], v169 offset:55296
	ds_read_b128 v[216:219], v169 offset:56320
	global_load_lds_dwordx4 v[162:163], off
	s_add_i32 m0, s50, 0x2000
	s_add_u32 s48, s48, 0x40080
	v_lshl_add_u64 v[162:163], v[220:221], 0, s[18:19]
	s_addc_u32 s49, s49, 0
	s_add_i32 s50, s75, s57
	global_load_lds_dwordx4 v[162:163], off
	v_lshl_add_u64 v[162:163], s[48:49], 0, v[130:131]
	s_mov_b32 m0, s50
	s_nop 0
	global_load_lds_dwordx4 v[162:163], off
	v_lshl_add_u64 v[162:163], s[48:49], 0, v[134:135]
	s_add_i32 m0, s50, 0x2000
	s_nop 0
	global_load_lds_dwordx4 v[162:163], off
	v_lshl_add_u64 v[162:163], v[222:223], 0, s[18:19]
	s_mov_b32 m0, s33
	s_nop 0
	global_load_lds_dwordx4 v[162:163], off
	v_lshl_add_u64 v[162:163], v[224:225], 0, s[18:19]
	s_mov_b32 m0, s62
	s_nop 0
	global_load_lds_dwordx4 v[162:163], off
	s_waitcnt vmcnt(8)
	s_waitcnt lgkmcnt(0)
	s_barrier
	s_setprio 1
	s_waitcnt lgkmcnt(0)
	v_mfma_f32_16x16x32_bf16 v[60:63], v[146:149], v[188:191], v[60:63]
	v_mfma_f32_16x16x32_bf16 v[44:47], v[146:149], v[196:199], v[44:47]
	v_mfma_f32_16x16x32_bf16 v[28:31], v[146:149], v[204:207], v[28:31]
	v_mfma_f32_16x16x32_bf16 v[12:15], v[146:149], v[212:215], v[12:15]
	v_mfma_f32_16x16x32_bf16 v[8:11], v[154:157], v[212:215], v[8:11]
	v_mfma_f32_16x16x32_bf16 v[24:27], v[154:157], v[204:207], v[24:27]
	v_mfma_f32_16x16x32_bf16 v[40:43], v[154:157], v[196:199], v[40:43]
	v_mfma_f32_16x16x32_bf16 v[56:59], v[154:157], v[188:191], v[56:59]
	v_mfma_f32_16x16x32_bf16 v[60:63], v[150:153], v[192:195], v[60:63]
	v_mfma_f32_16x16x32_bf16 v[44:47], v[150:153], v[200:203], v[44:47]
	v_mfma_f32_16x16x32_bf16 v[28:31], v[150:153], v[208:211], v[28:31]
	v_mfma_f32_16x16x32_bf16 v[12:15], v[150:153], v[216:219], v[12:15]
	v_mfma_f32_16x16x32_bf16 v[8:11], v[158:161], v[216:219], v[8:11]
	v_mfma_f32_16x16x32_bf16 v[24:27], v[158:161], v[208:211], v[24:27]
	v_mfma_f32_16x16x32_bf16 v[40:43], v[158:161], v[200:203], v[40:43]
	v_mfma_f32_16x16x32_bf16 v[56:59], v[158:161], v[192:195], v[56:59]
	s_setprio 0
	s_setprio 1
	v_mfma_f32_16x16x32_bf16 v[52:55], v[172:175], v[188:191], v[52:55]
	v_mfma_f32_16x16x32_bf16 v[36:39], v[172:175], v[196:199], v[36:39]
	v_mfma_f32_16x16x32_bf16 v[20:23], v[172:175], v[204:207], v[20:23]
	v_mfma_f32_16x16x32_bf16 v[4:7], v[172:175], v[212:215], v[4:7]
	v_mfma_f32_16x16x32_bf16 v[0:3], v[180:183], v[212:215], v[0:3]
	v_mfma_f32_16x16x32_bf16 v[16:19], v[180:183], v[204:207], v[16:19]
	v_mfma_f32_16x16x32_bf16 v[32:35], v[180:183], v[196:199], v[32:35]
	v_mfma_f32_16x16x32_bf16 v[48:51], v[180:183], v[188:191], v[48:51]
	v_mfma_f32_16x16x32_bf16 v[52:55], v[176:179], v[192:195], v[52:55]
	v_mfma_f32_16x16x32_bf16 v[36:39], v[176:179], v[200:203], v[36:39]
	v_mfma_f32_16x16x32_bf16 v[20:23], v[176:179], v[208:211], v[20:23]
	v_mfma_f32_16x16x32_bf16 v[4:7], v[176:179], v[216:219], v[4:7]
	v_mfma_f32_16x16x32_bf16 v[0:3], v[184:187], v[216:219], v[0:3]
	v_mfma_f32_16x16x32_bf16 v[16:19], v[184:187], v[208:211], v[16:19]
	v_mfma_f32_16x16x32_bf16 v[32:35], v[184:187], v[200:203], v[32:35]
	v_mfma_f32_16x16x32_bf16 v[48:51], v[184:187], v[192:195], v[48:51]
	s_setprio 0
	s_barrier
	s_add_i32 s73, s73, 2
	s_add_u32 s46, s46, 0x100
	s_addc_u32 s47, s47, 0
	s_add_u32 s53, s53, 0x100
	s_addc_u32 s72, s72, 0
	s_cmp_gt_u32 s73, 13
	s_cbranch_scc0 .LBB0_445
	s_and_b64 vcc, exec, s[20:21]
	s_cbranch_vccz .LBB0_448
	s_barrier

.LBB0_771:
	ds_read_b128 v[144:147], v174
	ds_read_b128 v[148:151], v174 offset:1024
	ds_read_b128 v[152:155], v174 offset:2048
	ds_read_b128 v[156:159], v174 offset:3072
	ds_read_b128 v[160:163], v175
	ds_read_b128 v[164:167], v175 offset:1024
	ds_read_b128 v[178:181], v175 offset:2048
	ds_read_b128 v[182:185], v175 offset:3072
	s_add_u32 s48, s46, 0xfffc0080
	s_addc_u32 s49, s47, -1
	s_cmp_eq_u32 s71, 12
	s_cselect_b32 s51, s1, s49
	s_cselect_b32 s50, s7, s48
	s_cselect_b32 s49, s33, s70
	s_cselect_b32 s48, s39, s41
	v_lshl_add_u64 v[168:169], s[46:47], 0, v[136:137]
	s_add_i32 m0, s56, 0xc000
	ds_read_b128 v[186:189], v176
	ds_read_b128 v[190:193], v176 offset:1024
	ds_read_b128 v[194:197], v176 offset:2048
	ds_read_b128 v[198:201], v176 offset:3072
	ds_read_b128 v[202:205], v176 offset:4096
	ds_read_b128 v[206:209], v176 offset:5120
	ds_read_b128 v[210:213], v176 offset:6144
	ds_read_b128 v[214:217], v176 offset:7168
	global_load_lds_dwordx4 v[168:169], off
	v_lshl_add_u64 v[168:169], s[46:47], 0, v[138:139]
	s_add_i32 m0, s56, 0xe000
	s_nop 0
	global_load_lds_dwordx4 v[168:169], off
	s_waitcnt vmcnt(8)
	s_waitcnt lgkmcnt(0)
	s_barrier
	s_setprio 1
	s_waitcnt lgkmcnt(0)
	v_mfma_f32_16x16x32_bf16 v[124:127], v[144:147], v[186:189], v[124:127]
	v_mfma_f32_16x16x32_bf16 v[108:111], v[144:147], v[194:197], v[108:111]
	v_mfma_f32_16x16x32_bf16 v[92:95], v[144:147], v[202:205], v[92:95]
	v_mfma_f32_16x16x32_bf16 v[76:79], v[144:147], v[210:213], v[76:79]
	v_mfma_f32_16x16x32_bf16 v[72:75], v[152:155], v[210:213], v[72:75]
	v_mfma_f32_16x16x32_bf16 v[88:91], v[152:155], v[202:205], v[88:91]
	v_mfma_f32_16x16x32_bf16 v[104:107], v[152:155], v[194:197], v[104:107]
	v_mfma_f32_16x16x32_bf16 v[120:123], v[152:155], v[186:189], v[120:123]
	v_mfma_f32_16x16x32_bf16 v[124:127], v[148:151], v[190:193], v[124:127]
	v_mfma_f32_16x16x32_bf16 v[108:111], v[148:151], v[198:201], v[108:111]
	v_mfma_f32_16x16x32_bf16 v[92:95], v[148:151], v[206:209], v[92:95]
	v_mfma_f32_16x16x32_bf16 v[76:79], v[148:151], v[214:217], v[76:79]
	v_mfma_f32_16x16x32_bf16 v[72:75], v[156:159], v[214:217], v[72:75]
	v_mfma_f32_16x16x32_bf16 v[88:91], v[156:159], v[206:209], v[88:91]
	v_mfma_f32_16x16x32_bf16 v[104:107], v[156:159], v[198:201], v[104:107]
	v_mfma_f32_16x16x32_bf16 v[120:123], v[156:159], v[190:193], v[120:123]
	s_setprio 0
	s_setprio 1
	v_mfma_f32_16x16x32_bf16 v[116:119], v[160:163], v[186:189], v[116:119]
	v_mfma_f32_16x16x32_bf16 v[100:103], v[160:163], v[194:197], v[100:103]
	v_mfma_f32_16x16x32_bf16 v[84:87], v[160:163], v[202:205], v[84:87]
	v_mfma_f32_16x16x32_bf16 v[68:71], v[160:163], v[210:213], v[68:71]
	v_mfma_f32_16x16x32_bf16 v[64:67], v[178:181], v[210:213], v[64:67]
	v_mfma_f32_16x16x32_bf16 v[80:83], v[178:181], v[202:205], v[80:83]
	v_mfma_f32_16x16x32_bf16 v[96:99], v[178:181], v[194:197], v[96:99]
	v_mfma_f32_16x16x32_bf16 v[112:115], v[178:181], v[186:189], v[112:115]
	v_mfma_f32_16x16x32_bf16 v[116:119], v[164:167], v[190:193], v[116:119]
	v_mfma_f32_16x16x32_bf16 v[100:103], v[164:167], v[198:201], v[100:103]
	v_mfma_f32_16x16x32_bf16 v[84:87], v[164:167], v[206:209], v[84:87]
	v_mfma_f32_16x16x32_bf16 v[68:71], v[164:167], v[214:217], v[68:71]
	v_mfma_f32_16x16x32_bf16 v[64:67], v[182:185], v[214:217], v[64:67]
	v_mfma_f32_16x16x32_bf16 v[80:83], v[182:185], v[206:209], v[80:83]
	v_mfma_f32_16x16x32_bf16 v[96:99], v[182:185], v[198:201], v[96:99]
	v_mfma_f32_16x16x32_bf16 v[112:115], v[182:185], v[190:193], v[112:115]
	s_setprio 0
	s_barrier
	s_add_i32 s72, s67, s55
	v_lshl_add_u64 v[168:169], s[48:49], 0, v[130:131]
	s_mov_b32 m0, s72
	ds_read_b128 v[186:189], v176 offset:16384
	ds_read_b128 v[190:193], v176 offset:17408
	ds_read_b128 v[194:197], v176 offset:18432
	ds_read_b128 v[198:201], v176 offset:19456
	ds_read_b128 v[202:205], v176 offset:20480
	ds_read_b128 v[206:209], v176 offset:21504
	ds_read_b128 v[210:213], v176 offset:22528
	ds_read_b128 v[214:217], v176 offset:23552
	global_load_lds_dwordx4 v[168:169], off
	s_add_i32 m0, s72, 0x2000
	s_add_u32 s72, s48, 0x40000
	v_lshl_add_u64 v[218:219], s[48:49], 0, v[134:135]
	s_addc_u32 s73, s49, 0
	s_add_i32 s74, s68, s55
	global_load_lds_dwordx4 v[218:219], off
	v_lshl_add_u64 v[220:221], s[72:73], 0, v[130:131]
	s_mov_b32 m0, s74
	v_lshl_add_u64 v[222:223], s[50:51], 0, v[132:133]
	global_load_lds_dwordx4 v[220:221], off
	v_lshl_add_u64 v[220:221], s[72:73], 0, v[134:135]
	s_add_i32 m0, s74, 0x2000
	s_nop 0
	global_load_lds_dwordx4 v[220:221], off
	v_lshl_add_u64 v[220:221], s[50:51], 0, v[128:129]
	s_mov_b32 m0, s56
	s_nop 0
	global_load_lds_dwordx4 v[220:221], off
	s_mov_b32 m0, s57
	s_nop 0
	global_load_lds_dwordx4 v[222:223], off
	s_waitcnt vmcnt(8)
	s_waitcnt lgkmcnt(0)
	s_barrier
	s_setprio 1
	s_waitcnt lgkmcnt(0)
	v_mfma_f32_16x16x32_bf16 v[60:63], v[144:147], v[186:189], v[60:63]
	v_mfma_f32_16x16x32_bf16 v[44:47], v[144:147], v[194:197], v[44:47]
	v_mfma_f32_16x16x32_bf16 v[28:31], v[144:147], v[202:205], v[28:31]
	v_mfma_f32_16x16x32_bf16 v[12:15], v[144:147], v[210:213], v[12:15]
	v_mfma_f32_16x16x32_bf16 v[8:11], v[152:155], v[210:213], v[8:11]
	v_mfma_f32_16x16x32_bf16 v[24:27], v[152:155], v[202:205], v[24:27]
	v_mfma_f32_16x16x32_bf16 v[40:43], v[152:155], v[194:197], v[40:43]
	v_mfma_f32_16x16x32_bf16 v[56:59], v[152:155], v[186:189], v[56:59]
	v_mfma_f32_16x16x32_bf16 v[60:63], v[148:151], v[190:193], v[60:63]
	v_mfma_f32_16x16x32_bf16 v[44:47], v[148:151], v[198:201], v[44:47]
	v_mfma_f32_16x16x32_bf16 v[28:31], v[148:151], v[206:209], v[28:31]
	v_mfma_f32_16x16x32_bf16 v[12:15], v[148:151], v[214:217], v[12:15]
	v_mfma_f32_16x16x32_bf16 v[8:11], v[156:159], v[214:217], v[8:11]
	v_mfma_f32_16x16x32_bf16 v[24:27], v[156:159], v[206:209], v[24:27]
	v_mfma_f32_16x16x32_bf16 v[40:43], v[156:159], v[198:201], v[40:43]
	v_mfma_f32_16x16x32_bf16 v[56:59], v[156:159], v[190:193], v[56:59]
	s_setprio 0
	s_setprio 1
	v_mfma_f32_16x16x32_bf16 v[52:55], v[160:163], v[186:189], v[52:55]
	v_mfma_f32_16x16x32_bf16 v[36:39], v[160:163], v[194:197], v[36:39]
	v_mfma_f32_16x16x32_bf16 v[20:23], v[160:163], v[202:205], v[20:23]
	v_mfma_f32_16x16x32_bf16 v[4:7], v[160:163], v[210:213], v[4:7]
	v_mfma_f32_16x16x32_bf16 v[0:3], v[178:181], v[210:213], v[0:3]
	v_mfma_f32_16x16x32_bf16 v[16:19], v[178:181], v[202:205], v[16:19]
	v_mfma_f32_16x16x32_bf16 v[32:35], v[178:181], v[194:197], v[32:35]
	v_mfma_f32_16x16x32_bf16 v[48:51], v[178:181], v[186:189], v[48:51]
	v_mfma_f32_16x16x32_bf16 v[52:55], v[164:167], v[190:193], v[52:55]
	v_mfma_f32_16x16x32_bf16 v[36:39], v[164:167], v[198:201], v[36:39]
	v_mfma_f32_16x16x32_bf16 v[20:23], v[164:167], v[206:209], v[20:23]
	v_mfma_f32_16x16x32_bf16 v[4:7], v[164:167], v[214:217], v[4:7]
	v_mfma_f32_16x16x32_bf16 v[0:3], v[182:185], v[214:217], v[0:3]
	v_mfma_f32_16x16x32_bf16 v[16:19], v[182:185], v[206:209], v[16:19]
	v_mfma_f32_16x16x32_bf16 v[32:35], v[182:185], v[198:201], v[32:35]
	v_mfma_f32_16x16x32_bf16 v[48:51], v[182:185], v[190:193], v[48:51]
	s_setprio 0
	s_barrier
	s_cmp_lg_u32 s71, 12
	s_cbranch_scc1 .Lmy_rs8_skip
	v_lshl_add_u32 v230, s6, 8, v171
	v_ashrrev_i32_e32 v231, 31, v230
	v_lshl_add_u64 v[232:233], v[230:231], 2, s[12:13]
	global_load_dword v230, v[232:233], off
	global_load_dword v234, v[232:233], off offset:128
	global_load_dword v236, v[232:233], off offset:192
	global_load_dword v238, v[232:233], off offset:512
	global_load_dword v240, v[232:233], off offset:576
	global_load_dword v242, v[232:233], off offset:640
	global_load_dword v244, v[232:233], off offset:704
	global_load_dword v232, v[232:233], off offset:64

.Lmy_rs8_wd:
	s_waitcnt lgkmcnt(0)
	s_barrier
	s_setprio 1
	s_waitcnt lgkmcnt(0)
	v_mfma_f32_16x16x32_bf16 v[124:127], v[144:147], v[186:189], v[124:127]
	v_mfma_f32_16x16x32_bf16 v[108:111], v[144:147], v[194:197], v[108:111]
	v_mfma_f32_16x16x32_bf16 v[92:95], v[144:147], v[202:205], v[92:95]
	v_mfma_f32_16x16x32_bf16 v[76:79], v[144:147], v[210:213], v[76:79]
	v_mfma_f32_16x16x32_bf16 v[72:75], v[152:155], v[210:213], v[72:75]
	v_mfma_f32_16x16x32_bf16 v[88:91], v[152:155], v[202:205], v[88:91]
	v_mfma_f32_16x16x32_bf16 v[104:107], v[152:155], v[194:197], v[104:107]
	v_mfma_f32_16x16x32_bf16 v[120:123], v[152:155], v[186:189], v[120:123]
	v_mfma_f32_16x16x32_bf16 v[124:127], v[148:151], v[190:193], v[124:127]
	v_mfma_f32_16x16x32_bf16 v[108:111], v[148:151], v[198:201], v[108:111]
	v_mfma_f32_16x16x32_bf16 v[92:95], v[148:151], v[206:209], v[92:95]
	v_mfma_f32_16x16x32_bf16 v[76:79], v[148:151], v[214:217], v[76:79]
	v_mfma_f32_16x16x32_bf16 v[72:75], v[156:159], v[214:217], v[72:75]
	v_mfma_f32_16x16x32_bf16 v[88:91], v[156:159], v[206:209], v[88:91]
	v_mfma_f32_16x16x32_bf16 v[104:107], v[156:159], v[198:201], v[104:107]
	v_mfma_f32_16x16x32_bf16 v[120:123], v[156:159], v[190:193], v[120:123]
	s_setprio 0
	s_setprio 1
	v_mfma_f32_16x16x32_bf16 v[116:119], v[160:163], v[186:189], v[116:119]
	v_mfma_f32_16x16x32_bf16 v[100:103], v[160:163], v[194:197], v[100:103]
	v_mfma_f32_16x16x32_bf16 v[84:87], v[160:163], v[202:205], v[84:87]
	v_mfma_f32_16x16x32_bf16 v[68:71], v[160:163], v[210:213], v[68:71]
	v_mfma_f32_16x16x32_bf16 v[64:67], v[178:181], v[210:213], v[64:67]
	v_mfma_f32_16x16x32_bf16 v[80:83], v[178:181], v[202:205], v[80:83]
	v_mfma_f32_16x16x32_bf16 v[96:99], v[178:181], v[194:197], v[96:99]
	v_mfma_f32_16x16x32_bf16 v[112:115], v[178:181], v[186:189], v[112:115]
	v_mfma_f32_16x16x32_bf16 v[116:119], v[164:167], v[190:193], v[116:119]
	v_mfma_f32_16x16x32_bf16 v[100:103], v[164:167], v[198:201], v[100:103]
	v_mfma_f32_16x16x32_bf16 v[84:87], v[164:167], v[206:209], v[84:87]
	v_mfma_f32_16x16x32_bf16 v[68:71], v[164:167], v[214:217], v[68:71]
	v_mfma_f32_16x16x32_bf16 v[64:67], v[182:185], v[214:217], v[64:67]
	v_mfma_f32_16x16x32_bf16 v[80:83], v[182:185], v[206:209], v[80:83]
	v_mfma_f32_16x16x32_bf16 v[96:99], v[182:185], v[198:201], v[96:99]
	v_mfma_f32_16x16x32_bf16 v[112:115], v[182:185], v[190:193], v[112:115]
	s_setprio 0
	s_barrier
	s_add_i32 s50, s72, s55
	v_lshl_add_u64 v[168:169], v[168:169], 0, s[16:17]
	s_mov_b32 m0, s50
	ds_read_b128 v[186:189], v176 offset:49152
	ds_read_b128 v[190:193], v176 offset:50176
	ds_read_b128 v[194:197], v176 offset:51200
	ds_read_b128 v[198:201], v176 offset:52224
	ds_read_b128 v[202:205], v176 offset:53248
	ds_read_b128 v[206:209], v176 offset:54272
	ds_read_b128 v[210:213], v176 offset:55296
	ds_read_b128 v[214:217], v176 offset:56320
	global_load_lds_dwordx4 v[168:169], off
	s_add_i32 m0, s50, 0x2000
	s_add_u32 s48, s48, 0x40080
	v_lshl_add_u64 v[168:169], v[218:219], 0, s[16:17]
	s_addc_u32 s49, s49, 0
	s_add_i32 s50, s73, s55
	global_load_lds_dwordx4 v[168:169], off
	v_lshl_add_u64 v[168:169], s[48:49], 0, v[130:131]
	s_mov_b32 m0, s50
	s_nop 0
	global_load_lds_dwordx4 v[168:169], off
	v_lshl_add_u64 v[168:169], s[48:49], 0, v[134:135]
	s_add_i32 m0, s50, 0x2000
	s_nop 0
	global_load_lds_dwordx4 v[168:169], off
	v_lshl_add_u64 v[168:169], v[220:221], 0, s[16:17]
	s_mov_b32 m0, s61
	s_nop 0
	global_load_lds_dwordx4 v[168:169], off
	v_lshl_add_u64 v[168:169], v[222:223], 0, s[16:17]
	s_mov_b32 m0, s62
	s_nop 0
	global_load_lds_dwordx4 v[168:169], off
	s_waitcnt vmcnt(8)
	s_waitcnt lgkmcnt(0)
	s_barrier
	s_setprio 1
	s_waitcnt lgkmcnt(0)
	v_mfma_f32_16x16x32_bf16 v[60:63], v[144:147], v[186:189], v[60:63]
	v_mfma_f32_16x16x32_bf16 v[44:47], v[144:147], v[194:197], v[44:47]
	v_mfma_f32_16x16x32_bf16 v[28:31], v[144:147], v[202:205], v[28:31]
	v_mfma_f32_16x16x32_bf16 v[12:15], v[144:147], v[210:213], v[12:15]
	v_mfma_f32_16x16x32_bf16 v[8:11], v[152:155], v[210:213], v[8:11]
	v_mfma_f32_16x16x32_bf16 v[24:27], v[152:155], v[202:205], v[24:27]
	v_mfma_f32_16x16x32_bf16 v[40:43], v[152:155], v[194:197], v[40:43]
	v_mfma_f32_16x16x32_bf16 v[56:59], v[152:155], v[186:189], v[56:59]
	v_mfma_f32_16x16x32_bf16 v[60:63], v[148:151], v[190:193], v[60:63]
	v_mfma_f32_16x16x32_bf16 v[44:47], v[148:151], v[198:201], v[44:47]
	v_mfma_f32_16x16x32_bf16 v[28:31], v[148:151], v[206:209], v[28:31]
	v_mfma_f32_16x16x32_bf16 v[12:15], v[148:151], v[214:217], v[12:15]
	v_mfma_f32_16x16x32_bf16 v[8:11], v[156:159], v[214:217], v[8:11]
	v_mfma_f32_16x16x32_bf16 v[24:27], v[156:159], v[206:209], v[24:27]
	v_mfma_f32_16x16x32_bf16 v[40:43], v[156:159], v[198:201], v[40:43]
	v_mfma_f32_16x16x32_bf16 v[56:59], v[156:159], v[190:193], v[56:59]
	s_setprio 0
	s_setprio 1
	v_mfma_f32_16x16x32_bf16 v[52:55], v[160:163], v[186:189], v[52:55]
	v_mfma_f32_16x16x32_bf16 v[36:39], v[160:163], v[194:197], v[36:39]
	v_mfma_f32_16x16x32_bf16 v[20:23], v[160:163], v[202:205], v[20:23]
	v_mfma_f32_16x16x32_bf16 v[4:7], v[160:163], v[210:213], v[4:7]
	v_mfma_f32_16x16x32_bf16 v[0:3], v[178:181], v[210:213], v[0:3]
	v_mfma_f32_16x16x32_bf16 v[16:19], v[178:181], v[202:205], v[16:19]
	v_mfma_f32_16x16x32_bf16 v[32:35], v[178:181], v[194:197], v[32:35]
	v_mfma_f32_16x16x32_bf16 v[48:51], v[178:181], v[186:189], v[48:51]
	v_mfma_f32_16x16x32_bf16 v[52:55], v[164:167], v[190:193], v[52:55]
	v_mfma_f32_16x16x32_bf16 v[36:39], v[164:167], v[198:201], v[36:39]
	v_mfma_f32_16x16x32_bf16 v[20:23], v[164:167], v[206:209], v[20:23]
	v_mfma_f32_16x16x32_bf16 v[4:7], v[164:167], v[214:217], v[4:7]
	v_mfma_f32_16x16x32_bf16 v[0:3], v[182:185], v[214:217], v[0:3]
	v_mfma_f32_16x16x32_bf16 v[16:19], v[182:185], v[206:209], v[16:19]
	v_mfma_f32_16x16x32_bf16 v[32:35], v[182:185], v[198:201], v[32:35]
	v_mfma_f32_16x16x32_bf16 v[48:51], v[182:185], v[190:193], v[48:51]
	s_setprio 0
	s_barrier
	s_add_i32 s71, s71, 2
	s_add_u32 s46, s46, 0x100
	s_addc_u32 s47, s47, 0
	s_add_u32 s41, s41, 0x100
	s_addc_u32 s70, s70, 0
	s_cmp_gt_u32 s71, 13
	s_cbranch_scc0 .LBB0_771
	s_and_b64 vcc, exec, s[18:19]
	s_cbranch_vccz .LBB0_774
	s_barrier

.LBB0_1033:
	ds_read_b128 v[144:147], v151
	ds_read_b128 v[162:165], v151 offset:1024
	ds_read_b128 v[166:169], v151 offset:2048
	ds_read_b128 v[172:175], v151 offset:3072
	ds_read_b128 v[176:179], v160
	ds_read_b128 v[180:183], v160 offset:1024
	ds_read_b128 v[184:187], v160 offset:2048
	ds_read_b128 v[188:191], v160 offset:3072
	s_add_u32 s42, s40, 0xfffc0080
	s_addc_u32 s43, s41, -1
	s_cmp_eq_u32 s65, 12
	s_cselect_b32 s45, s1, s43
	s_cselect_b32 s44, s35, s42
	s_cselect_b32 s43, s27, s64
	s_cselect_b32 s42, s62, s63
	v_lshl_add_u64 v[224:225], s[40:41], 0, v[136:137]
	s_add_i32 m0, s11, 0xc000
	ds_read_b128 v[192:195], v161
	ds_read_b128 v[196:199], v161 offset:1024
	ds_read_b128 v[200:203], v161 offset:2048
	ds_read_b128 v[204:207], v161 offset:3072
	ds_read_b128 v[208:211], v161 offset:4096
	ds_read_b128 v[212:215], v161 offset:5120
	ds_read_b128 v[216:219], v161 offset:6144
	ds_read_b128 v[220:223], v161 offset:7168
	global_load_lds_dwordx4 v[224:225], off
	v_lshl_add_u64 v[224:225], s[40:41], 0, v[138:139]
	s_add_i32 m0, s11, 0xe000
	s_nop 0
	global_load_lds_dwordx4 v[224:225], off
	s_waitcnt vmcnt(8)
	s_waitcnt lgkmcnt(0)
	s_barrier
	s_setprio 1
	s_waitcnt lgkmcnt(0)
	v_mfma_f32_16x16x32_bf16 v[124:127], v[144:147], v[192:195], v[124:127]
	v_mfma_f32_16x16x32_bf16 v[108:111], v[144:147], v[200:203], v[108:111]
	v_mfma_f32_16x16x32_bf16 v[92:95], v[144:147], v[208:211], v[92:95]
	v_mfma_f32_16x16x32_bf16 v[76:79], v[144:147], v[216:219], v[76:79]
	v_mfma_f32_16x16x32_bf16 v[72:75], v[166:169], v[216:219], v[72:75]
	v_mfma_f32_16x16x32_bf16 v[88:91], v[166:169], v[208:211], v[88:91]
	v_mfma_f32_16x16x32_bf16 v[104:107], v[166:169], v[200:203], v[104:107]
	v_mfma_f32_16x16x32_bf16 v[120:123], v[166:169], v[192:195], v[120:123]
	v_mfma_f32_16x16x32_bf16 v[124:127], v[162:165], v[196:199], v[124:127]
	v_mfma_f32_16x16x32_bf16 v[108:111], v[162:165], v[204:207], v[108:111]
	v_mfma_f32_16x16x32_bf16 v[92:95], v[162:165], v[212:215], v[92:95]
	v_mfma_f32_16x16x32_bf16 v[76:79], v[162:165], v[220:223], v[76:79]
	v_mfma_f32_16x16x32_bf16 v[72:75], v[172:175], v[220:223], v[72:75]
	v_mfma_f32_16x16x32_bf16 v[88:91], v[172:175], v[212:215], v[88:91]
	v_mfma_f32_16x16x32_bf16 v[104:107], v[172:175], v[204:207], v[104:107]
	v_mfma_f32_16x16x32_bf16 v[120:123], v[172:175], v[196:199], v[120:123]
	s_setprio 0
	s_setprio 1
	v_mfma_f32_16x16x32_bf16 v[116:119], v[176:179], v[192:195], v[116:119]
	v_mfma_f32_16x16x32_bf16 v[100:103], v[176:179], v[200:203], v[100:103]
	v_mfma_f32_16x16x32_bf16 v[84:87], v[176:179], v[208:211], v[84:87]
	v_mfma_f32_16x16x32_bf16 v[68:71], v[176:179], v[216:219], v[68:71]
	v_mfma_f32_16x16x32_bf16 v[64:67], v[184:187], v[216:219], v[64:67]
	v_mfma_f32_16x16x32_bf16 v[80:83], v[184:187], v[208:211], v[80:83]
	v_mfma_f32_16x16x32_bf16 v[96:99], v[184:187], v[200:203], v[96:99]
	v_mfma_f32_16x16x32_bf16 v[112:115], v[184:187], v[192:195], v[112:115]
	v_mfma_f32_16x16x32_bf16 v[116:119], v[180:183], v[196:199], v[116:119]
	v_mfma_f32_16x16x32_bf16 v[100:103], v[180:183], v[204:207], v[100:103]
	v_mfma_f32_16x16x32_bf16 v[84:87], v[180:183], v[212:215], v[84:87]
	v_mfma_f32_16x16x32_bf16 v[68:71], v[180:183], v[220:223], v[68:71]
	v_mfma_f32_16x16x32_bf16 v[64:67], v[188:191], v[220:223], v[64:67]
	v_mfma_f32_16x16x32_bf16 v[80:83], v[188:191], v[212:215], v[80:83]
	v_mfma_f32_16x16x32_bf16 v[96:99], v[188:191], v[204:207], v[96:99]
	v_mfma_f32_16x16x32_bf16 v[112:115], v[188:191], v[196:199], v[112:115]
	s_setprio 0
	s_barrier
	s_add_i32 s66, s60, s47
	v_lshl_add_u64 v[224:225], s[42:43], 0, v[130:131]
	s_mov_b32 m0, s66
	ds_read_b128 v[192:195], v161 offset:16384
	ds_read_b128 v[196:199], v161 offset:17408
	ds_read_b128 v[200:203], v161 offset:18432
	ds_read_b128 v[204:207], v161 offset:19456
	ds_read_b128 v[208:211], v161 offset:20480
	ds_read_b128 v[212:215], v161 offset:21504
	ds_read_b128 v[216:219], v161 offset:22528
	ds_read_b128 v[220:223], v161 offset:23552
	global_load_lds_dwordx4 v[224:225], off
	s_add_i32 m0, s66, 0x2000
	s_add_u32 s66, s42, 0x40000
	v_lshl_add_u64 v[226:227], s[42:43], 0, v[134:135]
	s_addc_u32 s67, s43, 0
	s_add_i32 s68, s61, s47
	global_load_lds_dwordx4 v[226:227], off
	v_lshl_add_u64 v[228:229], s[66:67], 0, v[130:131]
	s_mov_b32 m0, s68
	v_lshl_add_u64 v[230:231], s[44:45], 0, v[132:133]
	global_load_lds_dwordx4 v[228:229], off
	v_lshl_add_u64 v[228:229], s[66:67], 0, v[134:135]
	s_add_i32 m0, s68, 0x2000
	s_nop 0
	global_load_lds_dwordx4 v[228:229], off
	v_lshl_add_u64 v[228:229], s[44:45], 0, v[128:129]
	s_mov_b32 m0, s11
	s_nop 0
	global_load_lds_dwordx4 v[228:229], off
	s_mov_b32 m0, s48
	s_nop 0
	global_load_lds_dwordx4 v[230:231], off
	s_waitcnt vmcnt(8)
	s_waitcnt lgkmcnt(0)
	s_barrier
	s_setprio 1
	s_waitcnt lgkmcnt(0)
	v_mfma_f32_16x16x32_bf16 v[60:63], v[144:147], v[192:195], v[60:63]
	v_mfma_f32_16x16x32_bf16 v[44:47], v[144:147], v[200:203], v[44:47]
	v_mfma_f32_16x16x32_bf16 v[28:31], v[144:147], v[208:211], v[28:31]
	v_mfma_f32_16x16x32_bf16 v[12:15], v[144:147], v[216:219], v[12:15]
	v_mfma_f32_16x16x32_bf16 v[8:11], v[166:169], v[216:219], v[8:11]
	v_mfma_f32_16x16x32_bf16 v[24:27], v[166:169], v[208:211], v[24:27]
	v_mfma_f32_16x16x32_bf16 v[40:43], v[166:169], v[200:203], v[40:43]
	v_mfma_f32_16x16x32_bf16 v[56:59], v[166:169], v[192:195], v[56:59]
	v_mfma_f32_16x16x32_bf16 v[60:63], v[162:165], v[196:199], v[60:63]
	v_mfma_f32_16x16x32_bf16 v[44:47], v[162:165], v[204:207], v[44:47]
	v_mfma_f32_16x16x32_bf16 v[28:31], v[162:165], v[212:215], v[28:31]
	v_mfma_f32_16x16x32_bf16 v[12:15], v[162:165], v[220:223], v[12:15]
	v_mfma_f32_16x16x32_bf16 v[8:11], v[172:175], v[220:223], v[8:11]
	v_mfma_f32_16x16x32_bf16 v[24:27], v[172:175], v[212:215], v[24:27]
	v_mfma_f32_16x16x32_bf16 v[40:43], v[172:175], v[204:207], v[40:43]
	v_mfma_f32_16x16x32_bf16 v[56:59], v[172:175], v[196:199], v[56:59]
	s_setprio 0
	s_setprio 1
	v_mfma_f32_16x16x32_bf16 v[52:55], v[176:179], v[192:195], v[52:55]
	v_mfma_f32_16x16x32_bf16 v[36:39], v[176:179], v[200:203], v[36:39]
	v_mfma_f32_16x16x32_bf16 v[20:23], v[176:179], v[208:211], v[20:23]
	v_mfma_f32_16x16x32_bf16 v[4:7], v[176:179], v[216:219], v[4:7]
	v_mfma_f32_16x16x32_bf16 v[0:3], v[184:187], v[216:219], v[0:3]
	v_mfma_f32_16x16x32_bf16 v[16:19], v[184:187], v[208:211], v[16:19]
	v_mfma_f32_16x16x32_bf16 v[32:35], v[184:187], v[200:203], v[32:35]
	v_mfma_f32_16x16x32_bf16 v[48:51], v[184:187], v[192:195], v[48:51]
	v_mfma_f32_16x16x32_bf16 v[52:55], v[180:183], v[196:199], v[52:55]
	v_mfma_f32_16x16x32_bf16 v[36:39], v[180:183], v[204:207], v[36:39]
	v_mfma_f32_16x16x32_bf16 v[20:23], v[180:183], v[212:215], v[20:23]
	v_mfma_f32_16x16x32_bf16 v[4:7], v[180:183], v[220:223], v[4:7]
	v_mfma_f32_16x16x32_bf16 v[0:3], v[188:191], v[220:223], v[0:3]
	v_mfma_f32_16x16x32_bf16 v[16:19], v[188:191], v[212:215], v[16:19]
	v_mfma_f32_16x16x32_bf16 v[32:35], v[188:191], v[204:207], v[32:35]
	v_mfma_f32_16x16x32_bf16 v[48:51], v[188:191], v[196:199], v[48:51]
	s_setprio 0
	s_barrier
	s_add_i32 s66, 0, 0x18000
	v_add_u32_e32 v171, s66, v149
	s_add_i32 s67, 0, 0x1c000
	ds_read_b128 v[144:147], v171
	ds_read_b128 v[162:165], v171 offset:1024
	ds_read_b128 v[166:169], v171 offset:2048
	ds_read_b128 v[172:175], v171 offset:3072
	v_add_u32_e32 v171, s67, v149
	ds_read_b128 v[176:179], v171
	ds_read_b128 v[180:183], v171 offset:1024
	ds_read_b128 v[184:187], v171 offset:2048
	ds_read_b128 v[188:191], v171 offset:3072
	s_add_u32 s44, s44, 0x40000
	s_addc_u32 s45, s45, 0
	s_mov_b32 m0, s49
	v_lshl_add_u64 v[232:233], s[44:45], 0, v[128:129]
	ds_read_b128 v[192:195], v161 offset:32768
	ds_read_b128 v[196:199], v161 offset:33792
	ds_read_b128 v[200:203], v161 offset:34816
	ds_read_b128 v[204:207], v161 offset:35840
	ds_read_b128 v[208:211], v161 offset:36864
	ds_read_b128 v[212:215], v161 offset:37888
	ds_read_b128 v[216:219], v161 offset:38912
	ds_read_b128 v[220:223], v161 offset:39936
	global_load_lds_dwordx4 v[232:233], off
	v_lshl_add_u64 v[232:233], s[44:45], 0, v[132:133]
	s_mov_b32 m0, s51
	s_nop 0
	global_load_lds_dwordx4 v[232:233], off
	s_waitcnt vmcnt(8)
	s_waitcnt lgkmcnt(0)
	s_barrier
	s_setprio 1
	s_waitcnt lgkmcnt(0)
	v_mfma_f32_16x16x32_bf16 v[124:127], v[144:147], v[192:195], v[124:127]
	v_mfma_f32_16x16x32_bf16 v[108:111], v[144:147], v[200:203], v[108:111]
	v_mfma_f32_16x16x32_bf16 v[92:95], v[144:147], v[208:211], v[92:95]
	v_mfma_f32_16x16x32_bf16 v[76:79], v[144:147], v[216:219], v[76:79]
	v_mfma_f32_16x16x32_bf16 v[72:75], v[166:169], v[216:219], v[72:75]
	v_mfma_f32_16x16x32_bf16 v[88:91], v[166:169], v[208:211], v[88:91]
	v_mfma_f32_16x16x32_bf16 v[104:107], v[166:169], v[200:203], v[104:107]
	v_mfma_f32_16x16x32_bf16 v[120:123], v[166:169], v[192:195], v[120:123]
	v_mfma_f32_16x16x32_bf16 v[124:127], v[162:165], v[196:199], v[124:127]
	v_mfma_f32_16x16x32_bf16 v[108:111], v[162:165], v[204:207], v[108:111]
	v_mfma_f32_16x16x32_bf16 v[92:95], v[162:165], v[212:215], v[92:95]
	v_mfma_f32_16x16x32_bf16 v[76:79], v[162:165], v[220:223], v[76:79]
	v_mfma_f32_16x16x32_bf16 v[72:75], v[172:175], v[220:223], v[72:75]
	v_mfma_f32_16x16x32_bf16 v[88:91], v[172:175], v[212:215], v[88:91]
	v_mfma_f32_16x16x32_bf16 v[104:107], v[172:175], v[204:207], v[104:107]
	v_mfma_f32_16x16x32_bf16 v[120:123], v[172:175], v[196:199], v[120:123]
	s_setprio 0
	s_setprio 1
	v_mfma_f32_16x16x32_bf16 v[116:119], v[176:179], v[192:195], v[116:119]
	v_mfma_f32_16x16x32_bf16 v[100:103], v[176:179], v[200:203], v[100:103]
	v_mfma_f32_16x16x32_bf16 v[84:87], v[176:179], v[208:211], v[84:87]
	v_mfma_f32_16x16x32_bf16 v[68:71], v[176:179], v[216:219], v[68:71]
	v_mfma_f32_16x16x32_bf16 v[64:67], v[184:187], v[216:219], v[64:67]
	v_mfma_f32_16x16x32_bf16 v[80:83], v[184:187], v[208:211], v[80:83]
	v_mfma_f32_16x16x32_bf16 v[96:99], v[184:187], v[200:203], v[96:99]
	v_mfma_f32_16x16x32_bf16 v[112:115], v[184:187], v[192:195], v[112:115]
	v_mfma_f32_16x16x32_bf16 v[116:119], v[180:183], v[196:199], v[116:119]
	v_mfma_f32_16x16x32_bf16 v[100:103], v[180:183], v[204:207], v[100:103]
	v_mfma_f32_16x16x32_bf16 v[84:87], v[180:183], v[212:215], v[84:87]
	v_mfma_f32_16x16x32_bf16 v[68:71], v[180:183], v[220:223], v[68:71]
	v_mfma_f32_16x16x32_bf16 v[64:67], v[188:191], v[220:223], v[64:67]
	v_mfma_f32_16x16x32_bf16 v[80:83], v[188:191], v[212:215], v[80:83]
	v_mfma_f32_16x16x32_bf16 v[96:99], v[188:191], v[204:207], v[96:99]
	v_mfma_f32_16x16x32_bf16 v[112:115], v[188:191], v[196:199], v[112:115]
	s_setprio 0
	s_barrier
	s_add_i32 s44, s66, s47
	v_lshl_add_u64 v[224:225], v[224:225], 0, s[14:15]
	s_mov_b32 m0, s44
	ds_read_b128 v[192:195], v161 offset:49152
	ds_read_b128 v[196:199], v161 offset:50176
	ds_read_b128 v[200:203], v161 offset:51200
	ds_read_b128 v[204:207], v161 offset:52224
	ds_read_b128 v[208:211], v161 offset:53248
	ds_read_b128 v[212:215], v161 offset:54272
	ds_read_b128 v[216:219], v161 offset:55296
	ds_read_b128 v[220:223], v161 offset:56320
	global_load_lds_dwordx4 v[224:225], off
	s_add_i32 m0, s44, 0x2000
	s_add_u32 s42, s42, 0x40080
	v_lshl_add_u64 v[224:225], v[226:227], 0, s[14:15]
	s_addc_u32 s43, s43, 0
	s_add_i32 s44, s67, s47
	global_load_lds_dwordx4 v[224:225], off
	v_lshl_add_u64 v[224:225], s[42:43], 0, v[130:131]
	s_mov_b32 m0, s44
	s_nop 0
	global_load_lds_dwordx4 v[224:225], off
	v_lshl_add_u64 v[224:225], s[42:43], 0, v[134:135]
	s_add_i32 m0, s44, 0x2000
	s_nop 0
	global_load_lds_dwordx4 v[224:225], off
	v_lshl_add_u64 v[224:225], v[228:229], 0, s[14:15]
	s_mov_b32 m0, s53
	s_nop 0
	global_load_lds_dwordx4 v[224:225], off
	v_lshl_add_u64 v[224:225], v[230:231], 0, s[14:15]
	s_mov_b32 m0, s54
	s_nop 0
	global_load_lds_dwordx4 v[224:225], off
	s_waitcnt vmcnt(8)
	s_waitcnt lgkmcnt(0)
	s_barrier
	s_setprio 1
	s_waitcnt lgkmcnt(0)
	v_mfma_f32_16x16x32_bf16 v[60:63], v[144:147], v[192:195], v[60:63]
	v_mfma_f32_16x16x32_bf16 v[44:47], v[144:147], v[200:203], v[44:47]
	v_mfma_f32_16x16x32_bf16 v[28:31], v[144:147], v[208:211], v[28:31]
	v_mfma_f32_16x16x32_bf16 v[12:15], v[144:147], v[216:219], v[12:15]
	v_mfma_f32_16x16x32_bf16 v[8:11], v[166:169], v[216:219], v[8:11]
	v_mfma_f32_16x16x32_bf16 v[24:27], v[166:169], v[208:211], v[24:27]
	v_mfma_f32_16x16x32_bf16 v[40:43], v[166:169], v[200:203], v[40:43]
	v_mfma_f32_16x16x32_bf16 v[56:59], v[166:169], v[192:195], v[56:59]
	v_mfma_f32_16x16x32_bf16 v[60:63], v[162:165], v[196:199], v[60:63]
	v_mfma_f32_16x16x32_bf16 v[44:47], v[162:165], v[204:207], v[44:47]
	v_mfma_f32_16x16x32_bf16 v[28:31], v[162:165], v[212:215], v[28:31]
	v_mfma_f32_16x16x32_bf16 v[12:15], v[162:165], v[220:223], v[12:15]
	v_mfma_f32_16x16x32_bf16 v[8:11], v[172:175], v[220:223], v[8:11]
	v_mfma_f32_16x16x32_bf16 v[24:27], v[172:175], v[212:215], v[24:27]
	v_mfma_f32_16x16x32_bf16 v[40:43], v[172:175], v[204:207], v[40:43]
	v_mfma_f32_16x16x32_bf16 v[56:59], v[172:175], v[196:199], v[56:59]
	s_setprio 0
	s_setprio 1
	v_mfma_f32_16x16x32_bf16 v[52:55], v[176:179], v[192:195], v[52:55]
	v_mfma_f32_16x16x32_bf16 v[36:39], v[176:179], v[200:203], v[36:39]
	v_mfma_f32_16x16x32_bf16 v[20:23], v[176:179], v[208:211], v[20:23]
	v_mfma_f32_16x16x32_bf16 v[4:7], v[176:179], v[216:219], v[4:7]
	v_mfma_f32_16x16x32_bf16 v[0:3], v[184:187], v[216:219], v[0:3]
	v_mfma_f32_16x16x32_bf16 v[16:19], v[184:187], v[208:211], v[16:19]
	v_mfma_f32_16x16x32_bf16 v[32:35], v[184:187], v[200:203], v[32:35]
	v_mfma_f32_16x16x32_bf16 v[48:51], v[184:187], v[192:195], v[48:51]
	v_mfma_f32_16x16x32_bf16 v[52:55], v[180:183], v[196:199], v[52:55]
	v_mfma_f32_16x16x32_bf16 v[36:39], v[180:183], v[204:207], v[36:39]
	v_mfma_f32_16x16x32_bf16 v[20:23], v[180:183], v[212:215], v[20:23]
	v_mfma_f32_16x16x32_bf16 v[4:7], v[180:183], v[220:223], v[4:7]
	v_mfma_f32_16x16x32_bf16 v[0:3], v[188:191], v[220:223], v[0:3]
	v_mfma_f32_16x16x32_bf16 v[16:19], v[188:191], v[212:215], v[16:19]
	v_mfma_f32_16x16x32_bf16 v[32:35], v[188:191], v[204:207], v[32:35]
	v_mfma_f32_16x16x32_bf16 v[48:51], v[188:191], v[196:199], v[48:51]
	s_setprio 0
	s_barrier
	s_add_i32 s65, s65, 2
	s_add_u32 s40, s40, 0x100
	s_addc_u32 s41, s41, 0
	s_add_u32 s63, s63, 0x100
	s_addc_u32 s64, s64, 0
	s_cmp_gt_u32 s65, 13
	s_cbranch_scc0 .LBB0_1033
	s_and_b64 vcc, exec, s[16:17]
	s_cbranch_vccz .LBB0_1036
	s_barrier

.LBB0_1091:
	ds_read_b128 v[144:147], v151
	ds_read_b128 v[162:165], v151 offset:1024
	ds_read_b128 v[166:169], v151 offset:2048
	ds_read_b128 v[172:175], v151 offset:3072
	ds_read_b128 v[176:179], v160
	ds_read_b128 v[180:183], v160 offset:1024
	ds_read_b128 v[184:187], v160 offset:2048
	ds_read_b128 v[188:191], v160 offset:3072
	s_add_u32 s46, s44, 0xfffc0080
	s_addc_u32 s47, s45, -1
	s_cmp_eq_u32 s71, 12
	s_cselect_b32 s49, s1, s47
	s_cselect_b32 s48, s33, s46
	s_cselect_b32 s47, s37, s70
	s_cselect_b32 s46, s39, s69
	v_lshl_add_u64 v[224:225], s[44:45], 0, v[136:137]
	s_add_i32 m0, s21, 0xc000
	ds_read_b128 v[192:195], v161
	ds_read_b128 v[196:199], v161 offset:1024
	ds_read_b128 v[200:203], v161 offset:2048
	ds_read_b128 v[204:207], v161 offset:3072
	ds_read_b128 v[208:211], v161 offset:4096
	ds_read_b128 v[212:215], v161 offset:5120
	ds_read_b128 v[216:219], v161 offset:6144
	ds_read_b128 v[220:223], v161 offset:7168
	global_load_lds_dwordx4 v[224:225], off
	v_lshl_add_u64 v[224:225], s[44:45], 0, v[138:139]
	s_add_i32 m0, s21, 0xe000
	s_nop 0
	global_load_lds_dwordx4 v[224:225], off
	s_waitcnt vmcnt(8)
	s_waitcnt lgkmcnt(0)
	s_barrier
	s_setprio 1
	s_waitcnt lgkmcnt(0)
	v_mfma_f32_16x16x32_bf16 v[124:127], v[144:147], v[192:195], v[124:127]
	v_mfma_f32_16x16x32_bf16 v[108:111], v[144:147], v[200:203], v[108:111]
	v_mfma_f32_16x16x32_bf16 v[92:95], v[144:147], v[208:211], v[92:95]
	v_mfma_f32_16x16x32_bf16 v[76:79], v[144:147], v[216:219], v[76:79]
	v_mfma_f32_16x16x32_bf16 v[72:75], v[166:169], v[216:219], v[72:75]
	v_mfma_f32_16x16x32_bf16 v[88:91], v[166:169], v[208:211], v[88:91]
	v_mfma_f32_16x16x32_bf16 v[104:107], v[166:169], v[200:203], v[104:107]
	v_mfma_f32_16x16x32_bf16 v[120:123], v[166:169], v[192:195], v[120:123]
	v_mfma_f32_16x16x32_bf16 v[124:127], v[162:165], v[196:199], v[124:127]
	v_mfma_f32_16x16x32_bf16 v[108:111], v[162:165], v[204:207], v[108:111]
	v_mfma_f32_16x16x32_bf16 v[92:95], v[162:165], v[212:215], v[92:95]
	v_mfma_f32_16x16x32_bf16 v[76:79], v[162:165], v[220:223], v[76:79]
	v_mfma_f32_16x16x32_bf16 v[72:75], v[172:175], v[220:223], v[72:75]
	v_mfma_f32_16x16x32_bf16 v[88:91], v[172:175], v[212:215], v[88:91]
	v_mfma_f32_16x16x32_bf16 v[104:107], v[172:175], v[204:207], v[104:107]
	v_mfma_f32_16x16x32_bf16 v[120:123], v[172:175], v[196:199], v[120:123]
	s_setprio 0
	s_setprio 1
	v_mfma_f32_16x16x32_bf16 v[116:119], v[176:179], v[192:195], v[116:119]
	v_mfma_f32_16x16x32_bf16 v[100:103], v[176:179], v[200:203], v[100:103]
	v_mfma_f32_16x16x32_bf16 v[84:87], v[176:179], v[208:211], v[84:87]
	v_mfma_f32_16x16x32_bf16 v[68:71], v[176:179], v[216:219], v[68:71]
	v_mfma_f32_16x16x32_bf16 v[64:67], v[184:187], v[216:219], v[64:67]
	v_mfma_f32_16x16x32_bf16 v[80:83], v[184:187], v[208:211], v[80:83]
	v_mfma_f32_16x16x32_bf16 v[96:99], v[184:187], v[200:203], v[96:99]
	v_mfma_f32_16x16x32_bf16 v[112:115], v[184:187], v[192:195], v[112:115]
	v_mfma_f32_16x16x32_bf16 v[116:119], v[180:183], v[196:199], v[116:119]
	v_mfma_f32_16x16x32_bf16 v[100:103], v[180:183], v[204:207], v[100:103]
	v_mfma_f32_16x16x32_bf16 v[84:87], v[180:183], v[212:215], v[84:87]
	v_mfma_f32_16x16x32_bf16 v[68:71], v[180:183], v[220:223], v[68:71]
	v_mfma_f32_16x16x32_bf16 v[64:67], v[188:191], v[220:223], v[64:67]
	v_mfma_f32_16x16x32_bf16 v[80:83], v[188:191], v[212:215], v[80:83]
	v_mfma_f32_16x16x32_bf16 v[96:99], v[188:191], v[204:207], v[96:99]
	v_mfma_f32_16x16x32_bf16 v[112:115], v[188:191], v[196:199], v[112:115]
	s_setprio 0
	s_barrier
	s_add_i32 s72, s67, s55
	v_lshl_add_u64 v[224:225], s[46:47], 0, v[130:131]
	s_mov_b32 m0, s72
	ds_read_b128 v[192:195], v161 offset:16384
	ds_read_b128 v[196:199], v161 offset:17408
	ds_read_b128 v[200:203], v161 offset:18432
	ds_read_b128 v[204:207], v161 offset:19456
	ds_read_b128 v[208:211], v161 offset:20480
	ds_read_b128 v[212:215], v161 offset:21504
	ds_read_b128 v[216:219], v161 offset:22528
	ds_read_b128 v[220:223], v161 offset:23552
	global_load_lds_dwordx4 v[224:225], off
	s_add_i32 m0, s72, 0x2000
	s_add_u32 s72, s46, 0x40000
	v_lshl_add_u64 v[226:227], s[46:47], 0, v[134:135]
	s_addc_u32 s73, s47, 0
	s_add_i32 s74, s68, s55
	global_load_lds_dwordx4 v[226:227], off
	v_lshl_add_u64 v[228:229], s[72:73], 0, v[130:131]
	s_mov_b32 m0, s74
	v_lshl_add_u64 v[230:231], s[48:49], 0, v[132:133]
	global_load_lds_dwordx4 v[228:229], off
	v_lshl_add_u64 v[228:229], s[72:73], 0, v[134:135]
	s_add_i32 m0, s74, 0x2000
	s_nop 0
	global_load_lds_dwordx4 v[228:229], off
	v_lshl_add_u64 v[228:229], s[48:49], 0, v[128:129]
	s_mov_b32 m0, s21
	s_nop 0
	global_load_lds_dwordx4 v[228:229], off
	s_mov_b32 m0, s56
	s_nop 0
	global_load_lds_dwordx4 v[230:231], off
	s_waitcnt vmcnt(8)
	s_waitcnt lgkmcnt(0)
	s_barrier
	s_setprio 1
	s_waitcnt lgkmcnt(0)
	v_mfma_f32_16x16x32_bf16 v[60:63], v[144:147], v[192:195], v[60:63]
	v_mfma_f32_16x16x32_bf16 v[44:47], v[144:147], v[200:203], v[44:47]
	v_mfma_f32_16x16x32_bf16 v[28:31], v[144:147], v[208:211], v[28:31]
	v_mfma_f32_16x16x32_bf16 v[12:15], v[144:147], v[216:219], v[12:15]
	v_mfma_f32_16x16x32_bf16 v[8:11], v[166:169], v[216:219], v[8:11]
	v_mfma_f32_16x16x32_bf16 v[24:27], v[166:169], v[208:211], v[24:27]
	v_mfma_f32_16x16x32_bf16 v[40:43], v[166:169], v[200:203], v[40:43]
	v_mfma_f32_16x16x32_bf16 v[56:59], v[166:169], v[192:195], v[56:59]
	v_mfma_f32_16x16x32_bf16 v[60:63], v[162:165], v[196:199], v[60:63]
	v_mfma_f32_16x16x32_bf16 v[44:47], v[162:165], v[204:207], v[44:47]
	v_mfma_f32_16x16x32_bf16 v[28:31], v[162:165], v[212:215], v[28:31]
	v_mfma_f32_16x16x32_bf16 v[12:15], v[162:165], v[220:223], v[12:15]
	v_mfma_f32_16x16x32_bf16 v[8:11], v[172:175], v[220:223], v[8:11]
	v_mfma_f32_16x16x32_bf16 v[24:27], v[172:175], v[212:215], v[24:27]
	v_mfma_f32_16x16x32_bf16 v[40:43], v[172:175], v[204:207], v[40:43]
	v_mfma_f32_16x16x32_bf16 v[56:59], v[172:175], v[196:199], v[56:59]
	s_setprio 0
	s_setprio 1
	v_mfma_f32_16x16x32_bf16 v[52:55], v[176:179], v[192:195], v[52:55]
	v_mfma_f32_16x16x32_bf16 v[36:39], v[176:179], v[200:203], v[36:39]
	v_mfma_f32_16x16x32_bf16 v[20:23], v[176:179], v[208:211], v[20:23]
	v_mfma_f32_16x16x32_bf16 v[4:7], v[176:179], v[216:219], v[4:7]
	v_mfma_f32_16x16x32_bf16 v[0:3], v[184:187], v[216:219], v[0:3]
	v_mfma_f32_16x16x32_bf16 v[16:19], v[184:187], v[208:211], v[16:19]
	v_mfma_f32_16x16x32_bf16 v[32:35], v[184:187], v[200:203], v[32:35]
	v_mfma_f32_16x16x32_bf16 v[48:51], v[184:187], v[192:195], v[48:51]
	v_mfma_f32_16x16x32_bf16 v[52:55], v[180:183], v[196:199], v[52:55]
	v_mfma_f32_16x16x32_bf16 v[36:39], v[180:183], v[204:207], v[36:39]
	v_mfma_f32_16x16x32_bf16 v[20:23], v[180:183], v[212:215], v[20:23]
	v_mfma_f32_16x16x32_bf16 v[4:7], v[180:183], v[220:223], v[4:7]
	v_mfma_f32_16x16x32_bf16 v[0:3], v[188:191], v[220:223], v[0:3]
	v_mfma_f32_16x16x32_bf16 v[16:19], v[188:191], v[212:215], v[16:19]
	v_mfma_f32_16x16x32_bf16 v[32:35], v[188:191], v[204:207], v[32:35]
	v_mfma_f32_16x16x32_bf16 v[48:51], v[188:191], v[196:199], v[48:51]
	s_setprio 0
	s_barrier
	s_add_i32 s72, 0, 0x18000
	v_add_u32_e32 v171, s72, v149
	s_add_i32 s73, 0, 0x1c000
	ds_read_b128 v[144:147], v171
	ds_read_b128 v[162:165], v171 offset:1024
	ds_read_b128 v[166:169], v171 offset:2048
	ds_read_b128 v[172:175], v171 offset:3072
	v_add_u32_e32 v171, s73, v149
	ds_read_b128 v[176:179], v171
	ds_read_b128 v[180:183], v171 offset:1024
	ds_read_b128 v[184:187], v171 offset:2048
	ds_read_b128 v[188:191], v171 offset:3072
	s_add_u32 s48, s48, 0x40000
	s_addc_u32 s49, s49, 0
	s_mov_b32 m0, s57
	v_lshl_add_u64 v[232:233], s[48:49], 0, v[128:129]
	ds_read_b128 v[192:195], v161 offset:32768
	ds_read_b128 v[196:199], v161 offset:33792
	ds_read_b128 v[200:203], v161 offset:34816
	ds_read_b128 v[204:207], v161 offset:35840
	ds_read_b128 v[208:211], v161 offset:36864
	ds_read_b128 v[212:215], v161 offset:37888
	ds_read_b128 v[216:219], v161 offset:38912
	ds_read_b128 v[220:223], v161 offset:39936
	global_load_lds_dwordx4 v[232:233], off
	v_lshl_add_u64 v[232:233], s[48:49], 0, v[132:133]
	s_mov_b32 m0, s60
	s_nop 0
	global_load_lds_dwordx4 v[232:233], off
	s_waitcnt vmcnt(8)
	s_waitcnt lgkmcnt(0)
	s_barrier
	s_setprio 1
	s_waitcnt lgkmcnt(0)
	v_mfma_f32_16x16x32_bf16 v[124:127], v[144:147], v[192:195], v[124:127]
	v_mfma_f32_16x16x32_bf16 v[108:111], v[144:147], v[200:203], v[108:111]
	v_mfma_f32_16x16x32_bf16 v[92:95], v[144:147], v[208:211], v[92:95]
	v_mfma_f32_16x16x32_bf16 v[76:79], v[144:147], v[216:219], v[76:79]
	v_mfma_f32_16x16x32_bf16 v[72:75], v[166:169], v[216:219], v[72:75]
	v_mfma_f32_16x16x32_bf16 v[88:91], v[166:169], v[208:211], v[88:91]
	v_mfma_f32_16x16x32_bf16 v[104:107], v[166:169], v[200:203], v[104:107]
	v_mfma_f32_16x16x32_bf16 v[120:123], v[166:169], v[192:195], v[120:123]
	v_mfma_f32_16x16x32_bf16 v[124:127], v[162:165], v[196:199], v[124:127]
	v_mfma_f32_16x16x32_bf16 v[108:111], v[162:165], v[204:207], v[108:111]
	v_mfma_f32_16x16x32_bf16 v[92:95], v[162:165], v[212:215], v[92:95]
	v_mfma_f32_16x16x32_bf16 v[76:79], v[162:165], v[220:223], v[76:79]
	v_mfma_f32_16x16x32_bf16 v[72:75], v[172:175], v[220:223], v[72:75]
	v_mfma_f32_16x16x32_bf16 v[88:91], v[172:175], v[212:215], v[88:91]
	v_mfma_f32_16x16x32_bf16 v[104:107], v[172:175], v[204:207], v[104:107]
	v_mfma_f32_16x16x32_bf16 v[120:123], v[172:175], v[196:199], v[120:123]
	s_setprio 0
	s_setprio 1
	v_mfma_f32_16x16x32_bf16 v[116:119], v[176:179], v[192:195], v[116:119]
	v_mfma_f32_16x16x32_bf16 v[100:103], v[176:179], v[200:203], v[100:103]
	v_mfma_f32_16x16x32_bf16 v[84:87], v[176:179], v[208:211], v[84:87]
	v_mfma_f32_16x16x32_bf16 v[68:71], v[176:179], v[216:219], v[68:71]
	v_mfma_f32_16x16x32_bf16 v[64:67], v[184:187], v[216:219], v[64:67]
	v_mfma_f32_16x16x32_bf16 v[80:83], v[184:187], v[208:211], v[80:83]
	v_mfma_f32_16x16x32_bf16 v[96:99], v[184:187], v[200:203], v[96:99]
	v_mfma_f32_16x16x32_bf16 v[112:115], v[184:187], v[192:195], v[112:115]
	v_mfma_f32_16x16x32_bf16 v[116:119], v[180:183], v[196:199], v[116:119]
	v_mfma_f32_16x16x32_bf16 v[100:103], v[180:183], v[204:207], v[100:103]
	v_mfma_f32_16x16x32_bf16 v[84:87], v[180:183], v[212:215], v[84:87]
	v_mfma_f32_16x16x32_bf16 v[68:71], v[180:183], v[220:223], v[68:71]
	v_mfma_f32_16x16x32_bf16 v[64:67], v[188:191], v[220:223], v[64:67]
	v_mfma_f32_16x16x32_bf16 v[80:83], v[188:191], v[212:215], v[80:83]
	v_mfma_f32_16x16x32_bf16 v[96:99], v[188:191], v[204:207], v[96:99]
	v_mfma_f32_16x16x32_bf16 v[112:115], v[188:191], v[196:199], v[112:115]
	s_setprio 0
	s_barrier
	s_add_i32 s48, s72, s55
	v_lshl_add_u64 v[224:225], v[224:225], 0, s[16:17]
	s_mov_b32 m0, s48
	ds_read_b128 v[192:195], v161 offset:49152
	ds_read_b128 v[196:199], v161 offset:50176
	ds_read_b128 v[200:203], v161 offset:51200
	ds_read_b128 v[204:207], v161 offset:52224
	ds_read_b128 v[208:211], v161 offset:53248
	ds_read_b128 v[212:215], v161 offset:54272
	ds_read_b128 v[216:219], v161 offset:55296
	ds_read_b128 v[220:223], v161 offset:56320
	global_load_lds_dwordx4 v[224:225], off
	s_add_i32 m0, s48, 0x2000
	s_add_u32 s46, s46, 0x40080
	v_lshl_add_u64 v[224:225], v[226:227], 0, s[16:17]
	s_addc_u32 s47, s47, 0
	s_add_i32 s48, s73, s55
	global_load_lds_dwordx4 v[224:225], off
	v_lshl_add_u64 v[224:225], s[46:47], 0, v[130:131]
	s_mov_b32 m0, s48
	s_nop 0
	global_load_lds_dwordx4 v[224:225], off
	v_lshl_add_u64 v[224:225], s[46:47], 0, v[134:135]
	s_add_i32 m0, s48, 0x2000
	s_nop 0
	global_load_lds_dwordx4 v[224:225], off
	v_lshl_add_u64 v[224:225], v[228:229], 0, s[16:17]
	s_mov_b32 m0, s62
	s_nop 0
	global_load_lds_dwordx4 v[224:225], off
	v_lshl_add_u64 v[224:225], v[230:231], 0, s[16:17]
	s_mov_b32 m0, s63
	s_nop 0
	global_load_lds_dwordx4 v[224:225], off
	s_waitcnt vmcnt(8)
	s_waitcnt lgkmcnt(0)
	s_barrier
	s_setprio 1
	s_waitcnt lgkmcnt(0)
	v_mfma_f32_16x16x32_bf16 v[60:63], v[144:147], v[192:195], v[60:63]
	v_mfma_f32_16x16x32_bf16 v[44:47], v[144:147], v[200:203], v[44:47]
	v_mfma_f32_16x16x32_bf16 v[28:31], v[144:147], v[208:211], v[28:31]
	v_mfma_f32_16x16x32_bf16 v[12:15], v[144:147], v[216:219], v[12:15]
	v_mfma_f32_16x16x32_bf16 v[8:11], v[166:169], v[216:219], v[8:11]
	v_mfma_f32_16x16x32_bf16 v[24:27], v[166:169], v[208:211], v[24:27]
	v_mfma_f32_16x16x32_bf16 v[40:43], v[166:169], v[200:203], v[40:43]
	v_mfma_f32_16x16x32_bf16 v[56:59], v[166:169], v[192:195], v[56:59]
	v_mfma_f32_16x16x32_bf16 v[60:63], v[162:165], v[196:199], v[60:63]
	v_mfma_f32_16x16x32_bf16 v[44:47], v[162:165], v[204:207], v[44:47]
	v_mfma_f32_16x16x32_bf16 v[28:31], v[162:165], v[212:215], v[28:31]
	v_mfma_f32_16x16x32_bf16 v[12:15], v[162:165], v[220:223], v[12:15]
	v_mfma_f32_16x16x32_bf16 v[8:11], v[172:175], v[220:223], v[8:11]
	v_mfma_f32_16x16x32_bf16 v[24:27], v[172:175], v[212:215], v[24:27]
	v_mfma_f32_16x16x32_bf16 v[40:43], v[172:175], v[204:207], v[40:43]
	v_mfma_f32_16x16x32_bf16 v[56:59], v[172:175], v[196:199], v[56:59]
	s_setprio 0
	s_setprio 1
	v_mfma_f32_16x16x32_bf16 v[52:55], v[176:179], v[192:195], v[52:55]
	v_mfma_f32_16x16x32_bf16 v[36:39], v[176:179], v[200:203], v[36:39]
	v_mfma_f32_16x16x32_bf16 v[20:23], v[176:179], v[208:211], v[20:23]
	v_mfma_f32_16x16x32_bf16 v[4:7], v[176:179], v[216:219], v[4:7]
	v_mfma_f32_16x16x32_bf16 v[0:3], v[184:187], v[216:219], v[0:3]
	v_mfma_f32_16x16x32_bf16 v[16:19], v[184:187], v[208:211], v[16:19]
	v_mfma_f32_16x16x32_bf16 v[32:35], v[184:187], v[200:203], v[32:35]
	v_mfma_f32_16x16x32_bf16 v[48:51], v[184:187], v[192:195], v[48:51]
	v_mfma_f32_16x16x32_bf16 v[52:55], v[180:183], v[196:199], v[52:55]
	v_mfma_f32_16x16x32_bf16 v[36:39], v[180:183], v[204:207], v[36:39]
	v_mfma_f32_16x16x32_bf16 v[20:23], v[180:183], v[212:215], v[20:23]
	v_mfma_f32_16x16x32_bf16 v[4:7], v[180:183], v[220:223], v[4:7]
	v_mfma_f32_16x16x32_bf16 v[0:3], v[188:191], v[220:223], v[0:3]
	v_mfma_f32_16x16x32_bf16 v[16:19], v[188:191], v[212:215], v[16:19]
	v_mfma_f32_16x16x32_bf16 v[32:35], v[188:191], v[204:207], v[32:35]
	v_mfma_f32_16x16x32_bf16 v[48:51], v[188:191], v[196:199], v[48:51]
	s_setprio 0
	s_barrier
	s_add_i32 s71, s71, 2
	s_add_u32 s44, s44, 0x100
	s_addc_u32 s45, s45, 0
	s_add_u32 s69, s69, 0x100
	s_addc_u32 s70, s70, 0
	s_cmp_gt_u32 s71, 13
	s_cbranch_scc0 .LBB0_1091
	s_and_b64 vcc, exec, s[18:19]
	s_cbranch_vccz .LBB0_1094
	s_barrier

.LBB0_1183:
	ds_read_b128 v[148:151], v164
	ds_read_b128 v[172:175], v164 offset:1024
	ds_read_b128 v[176:179], v164 offset:2048
	ds_read_b128 v[180:183], v164 offset:3072
	ds_read_b128 v[184:187], v165
	ds_read_b128 v[188:191], v165 offset:1024
	ds_read_b128 v[192:195], v165 offset:2048
	ds_read_b128 v[196:199], v165 offset:3072
	s_add_u32 s54, s52, 0xfffc0080
	s_addc_u32 s55, s53, -1
	s_cmp_eq_u32 s77, 12
	s_cselect_b32 s57, s45, s55
	s_cselect_b32 s56, s73, s54
	s_cselect_b32 s55, s43, s76
	s_cselect_b32 s54, s74, s75
	v_lshl_add_u64 v[168:169], s[52:53], 0, v[140:141]
	s_add_i32 m0, s51, 0xc000
	ds_read_b128 v[200:203], v166
	ds_read_b128 v[204:207], v166 offset:1024
	ds_read_b128 v[208:211], v166 offset:2048
	ds_read_b128 v[212:215], v166 offset:3072
	ds_read_b128 v[216:219], v166 offset:4096
	ds_read_b128 v[220:223], v166 offset:5120
	ds_read_b128 v[224:227], v166 offset:6144
	ds_read_b128 v[228:231], v166 offset:7168
	global_load_lds_dwordx4 v[168:169], off
	v_lshl_add_u64 v[168:169], s[52:53], 0, v[142:143]
	s_add_i32 m0, s51, 0xe000
	s_nop 0
	global_load_lds_dwordx4 v[168:169], off
	s_waitcnt vmcnt(8)
	s_waitcnt lgkmcnt(0)
	s_barrier
	s_setprio 1
	s_waitcnt lgkmcnt(0)
	v_mfma_f32_16x16x32_bf16 v[124:127], v[148:151], v[200:203], v[124:127]
	v_mfma_f32_16x16x32_bf16 v[108:111], v[148:151], v[208:211], v[108:111]
	v_mfma_f32_16x16x32_bf16 v[92:95], v[148:151], v[216:219], v[92:95]
	v_mfma_f32_16x16x32_bf16 v[76:79], v[148:151], v[224:227], v[76:79]
	v_mfma_f32_16x16x32_bf16 v[72:75], v[176:179], v[224:227], v[72:75]
	v_mfma_f32_16x16x32_bf16 v[88:91], v[176:179], v[216:219], v[88:91]
	v_mfma_f32_16x16x32_bf16 v[104:107], v[176:179], v[208:211], v[104:107]
	v_mfma_f32_16x16x32_bf16 v[120:123], v[176:179], v[200:203], v[120:123]
	v_mfma_f32_16x16x32_bf16 v[124:127], v[172:175], v[204:207], v[124:127]
	v_mfma_f32_16x16x32_bf16 v[108:111], v[172:175], v[212:215], v[108:111]
	v_mfma_f32_16x16x32_bf16 v[92:95], v[172:175], v[220:223], v[92:95]
	v_mfma_f32_16x16x32_bf16 v[76:79], v[172:175], v[228:231], v[76:79]
	v_mfma_f32_16x16x32_bf16 v[72:75], v[180:183], v[228:231], v[72:75]
	v_mfma_f32_16x16x32_bf16 v[88:91], v[180:183], v[220:223], v[88:91]
	v_mfma_f32_16x16x32_bf16 v[104:107], v[180:183], v[212:215], v[104:107]
	v_mfma_f32_16x16x32_bf16 v[120:123], v[180:183], v[204:207], v[120:123]
	s_setprio 0
	s_setprio 1
	v_mfma_f32_16x16x32_bf16 v[116:119], v[184:187], v[200:203], v[116:119]
	v_mfma_f32_16x16x32_bf16 v[100:103], v[184:187], v[208:211], v[100:103]
	v_mfma_f32_16x16x32_bf16 v[84:87], v[184:187], v[216:219], v[84:87]
	v_mfma_f32_16x16x32_bf16 v[68:71], v[184:187], v[224:227], v[68:71]
	v_mfma_f32_16x16x32_bf16 v[64:67], v[192:195], v[224:227], v[64:67]
	v_mfma_f32_16x16x32_bf16 v[80:83], v[192:195], v[216:219], v[80:83]
	v_mfma_f32_16x16x32_bf16 v[96:99], v[192:195], v[208:211], v[96:99]
	v_mfma_f32_16x16x32_bf16 v[112:115], v[192:195], v[200:203], v[112:115]
	v_mfma_f32_16x16x32_bf16 v[116:119], v[188:191], v[204:207], v[116:119]
	v_mfma_f32_16x16x32_bf16 v[100:103], v[188:191], v[212:215], v[100:103]
	v_mfma_f32_16x16x32_bf16 v[84:87], v[188:191], v[220:223], v[84:87]
	v_mfma_f32_16x16x32_bf16 v[68:71], v[188:191], v[228:231], v[68:71]
	v_mfma_f32_16x16x32_bf16 v[64:67], v[196:199], v[228:231], v[64:67]
	v_mfma_f32_16x16x32_bf16 v[80:83], v[196:199], v[220:223], v[80:83]
	v_mfma_f32_16x16x32_bf16 v[96:99], v[196:199], v[212:215], v[96:99]
	v_mfma_f32_16x16x32_bf16 v[112:115], v[196:199], v[204:207], v[112:115]
	s_setprio 0
	s_barrier
	s_add_i32 s78, s70, s61
	v_lshl_add_u64 v[168:169], s[54:55], 0, v[130:131]
	s_mov_b32 m0, s78
	ds_read_b128 v[200:203], v166 offset:16384
	ds_read_b128 v[204:207], v166 offset:17408
	ds_read_b128 v[208:211], v166 offset:18432
	ds_read_b128 v[212:215], v166 offset:19456
	ds_read_b128 v[216:219], v166 offset:20480
	ds_read_b128 v[220:223], v166 offset:21504
	ds_read_b128 v[224:227], v166 offset:22528
	ds_read_b128 v[228:231], v166 offset:23552
	global_load_lds_dwordx4 v[168:169], off
	s_add_i32 m0, s78, 0x2000
	s_add_u32 s78, s54, 0x40000
	v_lshl_add_u64 v[232:233], s[54:55], 0, v[134:135]
	s_addc_u32 s79, s55, 0
	s_add_i32 s80, s71, s61
	global_load_lds_dwordx4 v[232:233], off
	v_lshl_add_u64 v[234:235], s[78:79], 0, v[130:131]
	s_mov_b32 m0, s80
	v_lshl_add_u64 v[236:237], s[56:57], 0, v[132:133]
	global_load_lds_dwordx4 v[234:235], off
	v_lshl_add_u64 v[234:235], s[78:79], 0, v[134:135]
	s_add_i32 m0, s80, 0x2000
	s_nop 0
	global_load_lds_dwordx4 v[234:235], off
	v_lshl_add_u64 v[234:235], s[56:57], 0, v[128:129]
	s_mov_b32 m0, s51
	s_nop 0
	global_load_lds_dwordx4 v[234:235], off
	s_mov_b32 m0, s62
	s_nop 0
	global_load_lds_dwordx4 v[236:237], off
	s_waitcnt vmcnt(8)
	s_waitcnt lgkmcnt(0)
	s_barrier
	s_setprio 1
	s_waitcnt lgkmcnt(0)
	v_mfma_f32_16x16x32_bf16 v[60:63], v[148:151], v[200:203], v[60:63]
	v_mfma_f32_16x16x32_bf16 v[44:47], v[148:151], v[208:211], v[44:47]
	v_mfma_f32_16x16x32_bf16 v[28:31], v[148:151], v[216:219], v[28:31]
	v_mfma_f32_16x16x32_bf16 v[12:15], v[148:151], v[224:227], v[12:15]
	v_mfma_f32_16x16x32_bf16 v[8:11], v[176:179], v[224:227], v[8:11]
	v_mfma_f32_16x16x32_bf16 v[24:27], v[176:179], v[216:219], v[24:27]
	v_mfma_f32_16x16x32_bf16 v[40:43], v[176:179], v[208:211], v[40:43]
	v_mfma_f32_16x16x32_bf16 v[56:59], v[176:179], v[200:203], v[56:59]
	v_mfma_f32_16x16x32_bf16 v[60:63], v[172:175], v[204:207], v[60:63]
	v_mfma_f32_16x16x32_bf16 v[44:47], v[172:175], v[212:215], v[44:47]
	v_mfma_f32_16x16x32_bf16 v[28:31], v[172:175], v[220:223], v[28:31]
	v_mfma_f32_16x16x32_bf16 v[12:15], v[172:175], v[228:231], v[12:15]
	v_mfma_f32_16x16x32_bf16 v[8:11], v[180:183], v[228:231], v[8:11]
	v_mfma_f32_16x16x32_bf16 v[24:27], v[180:183], v[220:223], v[24:27]
	v_mfma_f32_16x16x32_bf16 v[40:43], v[180:183], v[212:215], v[40:43]
	v_mfma_f32_16x16x32_bf16 v[56:59], v[180:183], v[204:207], v[56:59]
	s_setprio 0
	s_setprio 1
	v_mfma_f32_16x16x32_bf16 v[52:55], v[184:187], v[200:203], v[52:55]
	v_mfma_f32_16x16x32_bf16 v[36:39], v[184:187], v[208:211], v[36:39]
	v_mfma_f32_16x16x32_bf16 v[20:23], v[184:187], v[216:219], v[20:23]
	v_mfma_f32_16x16x32_bf16 v[4:7], v[184:187], v[224:227], v[4:7]
	v_mfma_f32_16x16x32_bf16 v[0:3], v[192:195], v[224:227], v[0:3]
	v_mfma_f32_16x16x32_bf16 v[16:19], v[192:195], v[216:219], v[16:19]
	v_mfma_f32_16x16x32_bf16 v[32:35], v[192:195], v[208:211], v[32:35]
	v_mfma_f32_16x16x32_bf16 v[48:51], v[192:195], v[200:203], v[48:51]
	v_mfma_f32_16x16x32_bf16 v[52:55], v[188:191], v[204:207], v[52:55]
	v_mfma_f32_16x16x32_bf16 v[36:39], v[188:191], v[212:215], v[36:39]
	v_mfma_f32_16x16x32_bf16 v[20:23], v[188:191], v[220:223], v[20:23]
	v_mfma_f32_16x16x32_bf16 v[4:7], v[188:191], v[228:231], v[4:7]
	v_mfma_f32_16x16x32_bf16 v[0:3], v[196:199], v[228:231], v[0:3]
	v_mfma_f32_16x16x32_bf16 v[16:19], v[196:199], v[220:223], v[16:19]
	v_mfma_f32_16x16x32_bf16 v[32:35], v[196:199], v[212:215], v[32:35]
	v_mfma_f32_16x16x32_bf16 v[48:51], v[196:199], v[204:207], v[48:51]
	s_setprio 0
	s_barrier
	s_add_i32 s78, 0, 0x18000
	v_add_u32_e32 v138, s78, v163
	s_add_i32 s79, 0, 0x1c000
	ds_read_b128 v[148:151], v138
	ds_read_b128 v[172:175], v138 offset:1024
	ds_read_b128 v[176:179], v138 offset:2048
	ds_read_b128 v[180:183], v138 offset:3072
	v_add_u32_e32 v138, s79, v163
	ds_read_b128 v[184:187], v138
	ds_read_b128 v[188:191], v138 offset:1024
	ds_read_b128 v[192:195], v138 offset:2048
	ds_read_b128 v[196:199], v138 offset:3072
	s_add_u32 s56, s56, 0x40000
	s_addc_u32 s57, s57, 0
	s_mov_b32 m0, s63
	v_lshl_add_u64 v[238:239], s[56:57], 0, v[128:129]
	ds_read_b128 v[200:203], v166 offset:32768
	ds_read_b128 v[204:207], v166 offset:33792
	ds_read_b128 v[208:211], v166 offset:34816
	ds_read_b128 v[212:215], v166 offset:35840
	ds_read_b128 v[216:219], v166 offset:36864
	ds_read_b128 v[220:223], v166 offset:37888
	ds_read_b128 v[224:227], v166 offset:38912
	ds_read_b128 v[228:231], v166 offset:39936
	global_load_lds_dwordx4 v[238:239], off
	v_lshl_add_u64 v[238:239], s[56:57], 0, v[132:133]
	s_mov_b32 m0, s64
	s_nop 0
	global_load_lds_dwordx4 v[238:239], off
	s_waitcnt vmcnt(8)
	s_waitcnt lgkmcnt(0)
	s_barrier
	s_setprio 1
	s_waitcnt lgkmcnt(0)
	v_mfma_f32_16x16x32_bf16 v[124:127], v[148:151], v[200:203], v[124:127]
	v_mfma_f32_16x16x32_bf16 v[108:111], v[148:151], v[208:211], v[108:111]
	v_mfma_f32_16x16x32_bf16 v[92:95], v[148:151], v[216:219], v[92:95]
	v_mfma_f32_16x16x32_bf16 v[76:79], v[148:151], v[224:227], v[76:79]
	v_mfma_f32_16x16x32_bf16 v[72:75], v[176:179], v[224:227], v[72:75]
	v_mfma_f32_16x16x32_bf16 v[88:91], v[176:179], v[216:219], v[88:91]
	v_mfma_f32_16x16x32_bf16 v[104:107], v[176:179], v[208:211], v[104:107]
	v_mfma_f32_16x16x32_bf16 v[120:123], v[176:179], v[200:203], v[120:123]
	v_mfma_f32_16x16x32_bf16 v[124:127], v[172:175], v[204:207], v[124:127]
	v_mfma_f32_16x16x32_bf16 v[108:111], v[172:175], v[212:215], v[108:111]
	v_mfma_f32_16x16x32_bf16 v[92:95], v[172:175], v[220:223], v[92:95]
	v_mfma_f32_16x16x32_bf16 v[76:79], v[172:175], v[228:231], v[76:79]
	v_mfma_f32_16x16x32_bf16 v[72:75], v[180:183], v[228:231], v[72:75]
	v_mfma_f32_16x16x32_bf16 v[88:91], v[180:183], v[220:223], v[88:91]
	v_mfma_f32_16x16x32_bf16 v[104:107], v[180:183], v[212:215], v[104:107]
	v_mfma_f32_16x16x32_bf16 v[120:123], v[180:183], v[204:207], v[120:123]
	s_setprio 0
	s_setprio 1
	v_mfma_f32_16x16x32_bf16 v[116:119], v[184:187], v[200:203], v[116:119]
	v_mfma_f32_16x16x32_bf16 v[100:103], v[184:187], v[208:211], v[100:103]
	v_mfma_f32_16x16x32_bf16 v[84:87], v[184:187], v[216:219], v[84:87]
	v_mfma_f32_16x16x32_bf16 v[68:71], v[184:187], v[224:227], v[68:71]
	v_mfma_f32_16x16x32_bf16 v[64:67], v[192:195], v[224:227], v[64:67]
	v_mfma_f32_16x16x32_bf16 v[80:83], v[192:195], v[216:219], v[80:83]
	v_mfma_f32_16x16x32_bf16 v[96:99], v[192:195], v[208:211], v[96:99]
	v_mfma_f32_16x16x32_bf16 v[112:115], v[192:195], v[200:203], v[112:115]
	v_mfma_f32_16x16x32_bf16 v[116:119], v[188:191], v[204:207], v[116:119]
	v_mfma_f32_16x16x32_bf16 v[100:103], v[188:191], v[212:215], v[100:103]
	v_mfma_f32_16x16x32_bf16 v[84:87], v[188:191], v[220:223], v[84:87]
	v_mfma_f32_16x16x32_bf16 v[68:71], v[188:191], v[228:231], v[68:71]
	v_mfma_f32_16x16x32_bf16 v[64:67], v[196:199], v[228:231], v[64:67]
	v_mfma_f32_16x16x32_bf16 v[80:83], v[196:199], v[220:223], v[80:83]
	v_mfma_f32_16x16x32_bf16 v[96:99], v[196:199], v[212:215], v[96:99]
	v_mfma_f32_16x16x32_bf16 v[112:115], v[196:199], v[204:207], v[112:115]
	s_setprio 0
	s_barrier
	s_add_i32 s56, s78, s61
	v_lshl_add_u64 v[168:169], v[168:169], 0, s[18:19]
	s_mov_b32 m0, s56
	ds_read_b128 v[200:203], v166 offset:49152
	ds_read_b128 v[204:207], v166 offset:50176
	ds_read_b128 v[208:211], v166 offset:51200
	ds_read_b128 v[212:215], v166 offset:52224
	ds_read_b128 v[216:219], v166 offset:53248
	ds_read_b128 v[220:223], v166 offset:54272
	ds_read_b128 v[224:227], v166 offset:55296
	ds_read_b128 v[228:231], v166 offset:56320
	global_load_lds_dwordx4 v[168:169], off
	s_add_i32 m0, s56, 0x2000
	s_add_u32 s54, s54, 0x40080
	v_lshl_add_u64 v[168:169], v[232:233], 0, s[18:19]
	s_addc_u32 s55, s55, 0
	s_add_i32 s56, s79, s61
	global_load_lds_dwordx4 v[168:169], off
	v_lshl_add_u64 v[168:169], s[54:55], 0, v[130:131]
	s_mov_b32 m0, s56
	s_nop 0
	global_load_lds_dwordx4 v[168:169], off
	v_lshl_add_u64 v[168:169], s[54:55], 0, v[134:135]
	s_add_i32 m0, s56, 0x2000
	s_nop 0
	global_load_lds_dwordx4 v[168:169], off
	v_lshl_add_u64 v[168:169], v[234:235], 0, s[18:19]
	s_mov_b32 m0, s66
	s_nop 0
	global_load_lds_dwordx4 v[168:169], off
	v_lshl_add_u64 v[168:169], v[236:237], 0, s[18:19]
	s_mov_b32 m0, s67
	s_nop 0
	global_load_lds_dwordx4 v[168:169], off
	s_waitcnt vmcnt(8)
	s_waitcnt lgkmcnt(0)
	s_barrier
	s_setprio 1
	s_waitcnt lgkmcnt(0)
	v_mfma_f32_16x16x32_bf16 v[60:63], v[148:151], v[200:203], v[60:63]
	v_mfma_f32_16x16x32_bf16 v[44:47], v[148:151], v[208:211], v[44:47]
	v_mfma_f32_16x16x32_bf16 v[28:31], v[148:151], v[216:219], v[28:31]
	v_mfma_f32_16x16x32_bf16 v[12:15], v[148:151], v[224:227], v[12:15]
	v_mfma_f32_16x16x32_bf16 v[8:11], v[176:179], v[224:227], v[8:11]
	v_mfma_f32_16x16x32_bf16 v[24:27], v[176:179], v[216:219], v[24:27]
	v_mfma_f32_16x16x32_bf16 v[40:43], v[176:179], v[208:211], v[40:43]
	v_mfma_f32_16x16x32_bf16 v[56:59], v[176:179], v[200:203], v[56:59]
	v_mfma_f32_16x16x32_bf16 v[60:63], v[172:175], v[204:207], v[60:63]
	v_mfma_f32_16x16x32_bf16 v[44:47], v[172:175], v[212:215], v[44:47]
	v_mfma_f32_16x16x32_bf16 v[28:31], v[172:175], v[220:223], v[28:31]
	v_mfma_f32_16x16x32_bf16 v[12:15], v[172:175], v[228:231], v[12:15]
	v_mfma_f32_16x16x32_bf16 v[8:11], v[180:183], v[228:231], v[8:11]
	v_mfma_f32_16x16x32_bf16 v[24:27], v[180:183], v[220:223], v[24:27]
	v_mfma_f32_16x16x32_bf16 v[40:43], v[180:183], v[212:215], v[40:43]
	v_mfma_f32_16x16x32_bf16 v[56:59], v[180:183], v[204:207], v[56:59]
	s_setprio 0
	s_setprio 1
	v_mfma_f32_16x16x32_bf16 v[52:55], v[184:187], v[200:203], v[52:55]
	v_mfma_f32_16x16x32_bf16 v[36:39], v[184:187], v[208:211], v[36:39]
	v_mfma_f32_16x16x32_bf16 v[20:23], v[184:187], v[216:219], v[20:23]
	v_mfma_f32_16x16x32_bf16 v[4:7], v[184:187], v[224:227], v[4:7]
	v_mfma_f32_16x16x32_bf16 v[0:3], v[192:195], v[224:227], v[0:3]
	v_mfma_f32_16x16x32_bf16 v[16:19], v[192:195], v[216:219], v[16:19]
	v_mfma_f32_16x16x32_bf16 v[32:35], v[192:195], v[208:211], v[32:35]
	v_mfma_f32_16x16x32_bf16 v[48:51], v[192:195], v[200:203], v[48:51]
	v_mfma_f32_16x16x32_bf16 v[52:55], v[188:191], v[204:207], v[52:55]
	v_mfma_f32_16x16x32_bf16 v[36:39], v[188:191], v[212:215], v[36:39]
	v_mfma_f32_16x16x32_bf16 v[20:23], v[188:191], v[220:223], v[20:23]
	v_mfma_f32_16x16x32_bf16 v[4:7], v[188:191], v[228:231], v[4:7]
	v_mfma_f32_16x16x32_bf16 v[0:3], v[196:199], v[228:231], v[0:3]
	v_mfma_f32_16x16x32_bf16 v[16:19], v[196:199], v[220:223], v[16:19]
	v_mfma_f32_16x16x32_bf16 v[32:35], v[196:199], v[212:215], v[32:35]
	v_mfma_f32_16x16x32_bf16 v[48:51], v[196:199], v[204:207], v[48:51]
	s_setprio 0
	s_barrier
	s_add_i32 s77, s77, 2
	s_add_u32 s52, s52, 0x100
	s_addc_u32 s53, s53, 0
	s_add_u32 s75, s75, 0x100
	s_addc_u32 s76, s76, 0
	s_cmp_gt_u32 s77, 13
	s_cbranch_scc0 .LBB0_1183
	s_and_b64 vcc, exec, s[20:21]
	s_cbranch_vccz .LBB0_1186
	s_barrier

.LBB0_1269:
	ds_read_b128 v[154:157], v150
	ds_read_b128 v[158:161], v150 offset:1024
	ds_read_b128 v[162:165], v150 offset:2048
	ds_read_b128 v[166:169], v150 offset:3072
	ds_read_b128 v[172:175], v151
	ds_read_b128 v[176:179], v151 offset:1024
	ds_read_b128 v[180:183], v151 offset:2048
	ds_read_b128 v[184:187], v151 offset:3072
	s_add_u32 s40, s38, 0xfffc0080
	s_addc_u32 s41, s39, -1
	s_cmp_eq_u32 s69, 12
	s_cselect_b32 s43, s25, s41
	s_cselect_b32 s42, s37, s40
	s_cselect_b32 s41, s23, s68
	s_cselect_b32 s40, s66, s67
	v_lshl_add_u64 v[220:221], s[38:39], 0, v[138:139]
	s_add_i32 m0, s47, 0xc000
	ds_read_b128 v[188:191], v152
	ds_read_b128 v[192:195], v152 offset:1024
	ds_read_b128 v[196:199], v152 offset:2048
	ds_read_b128 v[200:203], v152 offset:3072
	ds_read_b128 v[204:207], v152 offset:4096
	ds_read_b128 v[208:211], v152 offset:5120
	ds_read_b128 v[212:215], v152 offset:6144
	ds_read_b128 v[216:219], v152 offset:7168
	global_load_lds_dwordx4 v[220:221], off
	v_lshl_add_u64 v[220:221], s[38:39], 0, v[140:141]
	s_add_i32 m0, s47, 0xe000
	s_nop 0
	global_load_lds_dwordx4 v[220:221], off
	s_waitcnt vmcnt(8)
	s_waitcnt lgkmcnt(0)
	s_barrier
	s_setprio 1
	s_waitcnt lgkmcnt(0)
	v_mfma_f32_16x16x32_bf16 v[124:127], v[154:157], v[188:191], v[124:127]
	v_mfma_f32_16x16x32_bf16 v[116:119], v[154:157], v[196:199], v[116:119]
	v_mfma_f32_16x16x32_bf16 v[108:111], v[154:157], v[204:207], v[108:111]
	v_mfma_f32_16x16x32_bf16 v[76:79], v[154:157], v[212:215], v[76:79]
	v_mfma_f32_16x16x32_bf16 v[72:75], v[162:165], v[212:215], v[72:75]
	v_mfma_f32_16x16x32_bf16 v[100:103], v[162:165], v[204:207], v[100:103]
	v_mfma_f32_16x16x32_bf16 v[112:115], v[162:165], v[196:199], v[112:115]
	v_mfma_f32_16x16x32_bf16 v[120:123], v[162:165], v[188:191], v[120:123]
	v_mfma_f32_16x16x32_bf16 v[124:127], v[158:161], v[192:195], v[124:127]
	v_mfma_f32_16x16x32_bf16 v[116:119], v[158:161], v[200:203], v[116:119]
	v_mfma_f32_16x16x32_bf16 v[108:111], v[158:161], v[208:211], v[108:111]
	v_mfma_f32_16x16x32_bf16 v[76:79], v[158:161], v[216:219], v[76:79]
	v_mfma_f32_16x16x32_bf16 v[72:75], v[166:169], v[216:219], v[72:75]
	v_mfma_f32_16x16x32_bf16 v[100:103], v[166:169], v[208:211], v[100:103]
	v_mfma_f32_16x16x32_bf16 v[112:115], v[166:169], v[200:203], v[112:115]
	v_mfma_f32_16x16x32_bf16 v[120:123], v[166:169], v[192:195], v[120:123]
	s_setprio 0
	s_setprio 1
	v_mfma_f32_16x16x32_bf16 v[104:107], v[172:175], v[188:191], v[104:107]
	v_mfma_f32_16x16x32_bf16 v[92:95], v[172:175], v[196:199], v[92:95]
	v_mfma_f32_16x16x32_bf16 v[84:87], v[172:175], v[204:207], v[84:87]
	v_mfma_f32_16x16x32_bf16 v[68:71], v[172:175], v[212:215], v[68:71]
	v_mfma_f32_16x16x32_bf16 v[64:67], v[180:183], v[212:215], v[64:67]
	v_mfma_f32_16x16x32_bf16 v[80:83], v[180:183], v[204:207], v[80:83]
	v_mfma_f32_16x16x32_bf16 v[88:91], v[180:183], v[196:199], v[88:91]
	v_mfma_f32_16x16x32_bf16 v[96:99], v[180:183], v[188:191], v[96:99]
	v_mfma_f32_16x16x32_bf16 v[104:107], v[176:179], v[192:195], v[104:107]
	v_mfma_f32_16x16x32_bf16 v[92:95], v[176:179], v[200:203], v[92:95]
	v_mfma_f32_16x16x32_bf16 v[84:87], v[176:179], v[208:211], v[84:87]
	v_mfma_f32_16x16x32_bf16 v[68:71], v[176:179], v[216:219], v[68:71]
	v_mfma_f32_16x16x32_bf16 v[64:67], v[184:187], v[216:219], v[64:67]
	v_mfma_f32_16x16x32_bf16 v[80:83], v[184:187], v[208:211], v[80:83]
	v_mfma_f32_16x16x32_bf16 v[88:91], v[184:187], v[200:203], v[88:91]
	v_mfma_f32_16x16x32_bf16 v[96:99], v[184:187], v[192:195], v[96:99]
	s_setprio 0
	s_barrier
	s_add_i32 s70, s56, s46
	v_lshl_add_u64 v[220:221], s[40:41], 0, v[130:131]
	s_mov_b32 m0, s70
	ds_read_b128 v[188:191], v152 offset:16384
	ds_read_b128 v[192:195], v152 offset:17408
	ds_read_b128 v[196:199], v152 offset:18432
	ds_read_b128 v[200:203], v152 offset:19456
	ds_read_b128 v[204:207], v152 offset:20480
	ds_read_b128 v[208:211], v152 offset:21504
	ds_read_b128 v[212:215], v152 offset:22528
	ds_read_b128 v[216:219], v152 offset:23552
	global_load_lds_dwordx4 v[220:221], off
	s_add_i32 m0, s70, 0x2000
	s_add_u32 s70, s40, 0x40000
	v_lshl_add_u64 v[222:223], s[40:41], 0, v[134:135]
	s_addc_u32 s71, s41, 0
	s_add_i32 s72, s57, s46
	global_load_lds_dwordx4 v[222:223], off
	v_lshl_add_u64 v[224:225], s[70:71], 0, v[130:131]
	s_mov_b32 m0, s72
	v_lshl_add_u64 v[226:227], s[42:43], 0, v[132:133]
	global_load_lds_dwordx4 v[224:225], off
	v_lshl_add_u64 v[224:225], s[70:71], 0, v[134:135]
	s_add_i32 m0, s72, 0x2000
	s_nop 0
	global_load_lds_dwordx4 v[224:225], off
	v_lshl_add_u64 v[224:225], s[42:43], 0, v[128:129]
	s_mov_b32 m0, s47
	s_nop 0
	global_load_lds_dwordx4 v[224:225], off
	s_mov_b32 m0, s48
	s_nop 0
	global_load_lds_dwordx4 v[226:227], off
	s_waitcnt vmcnt(8)
	s_waitcnt lgkmcnt(0)
	s_barrier
	s_setprio 1
	s_waitcnt lgkmcnt(0)
	v_mfma_f32_16x16x32_bf16 v[60:63], v[154:157], v[188:191], v[60:63]
	v_mfma_f32_16x16x32_bf16 v[52:55], v[154:157], v[196:199], v[52:55]
	v_mfma_f32_16x16x32_bf16 v[36:39], v[154:157], v[204:207], v[36:39]
	v_mfma_f32_16x16x32_bf16 v[20:23], v[154:157], v[212:215], v[20:23]
	v_mfma_f32_16x16x32_bf16 v[12:15], v[162:165], v[212:215], v[12:15]
	v_mfma_f32_16x16x32_bf16 v[28:31], v[162:165], v[204:207], v[28:31]
	v_mfma_f32_16x16x32_bf16 v[44:47], v[162:165], v[196:199], v[44:47]
	v_mfma_f32_16x16x32_bf16 v[56:59], v[162:165], v[188:191], v[56:59]
	v_mfma_f32_16x16x32_bf16 v[60:63], v[158:161], v[192:195], v[60:63]
	v_mfma_f32_16x16x32_bf16 v[52:55], v[158:161], v[200:203], v[52:55]
	v_mfma_f32_16x16x32_bf16 v[36:39], v[158:161], v[208:211], v[36:39]
	v_mfma_f32_16x16x32_bf16 v[20:23], v[158:161], v[216:219], v[20:23]
	v_mfma_f32_16x16x32_bf16 v[12:15], v[166:169], v[216:219], v[12:15]
	v_mfma_f32_16x16x32_bf16 v[28:31], v[166:169], v[208:211], v[28:31]
	v_mfma_f32_16x16x32_bf16 v[44:47], v[166:169], v[200:203], v[44:47]
	v_mfma_f32_16x16x32_bf16 v[56:59], v[166:169], v[192:195], v[56:59]
	s_setprio 0
	s_setprio 1
	v_mfma_f32_16x16x32_bf16 v[48:51], v[172:175], v[188:191], v[48:51]
	v_mfma_f32_16x16x32_bf16 v[32:35], v[172:175], v[196:199], v[32:35]
	v_mfma_f32_16x16x32_bf16 v[16:19], v[172:175], v[204:207], v[16:19]
	v_mfma_f32_16x16x32_bf16 v[4:7], v[172:175], v[212:215], v[4:7]
	v_mfma_f32_16x16x32_bf16 v[0:3], v[180:183], v[212:215], v[0:3]
	v_mfma_f32_16x16x32_bf16 v[8:11], v[180:183], v[204:207], v[8:11]
	v_mfma_f32_16x16x32_bf16 v[24:27], v[180:183], v[196:199], v[24:27]
	v_mfma_f32_16x16x32_bf16 v[40:43], v[180:183], v[188:191], v[40:43]
	v_mfma_f32_16x16x32_bf16 v[48:51], v[176:179], v[192:195], v[48:51]
	v_mfma_f32_16x16x32_bf16 v[32:35], v[176:179], v[200:203], v[32:35]
	v_mfma_f32_16x16x32_bf16 v[16:19], v[176:179], v[208:211], v[16:19]
	v_mfma_f32_16x16x32_bf16 v[4:7], v[176:179], v[216:219], v[4:7]
	v_mfma_f32_16x16x32_bf16 v[0:3], v[184:187], v[216:219], v[0:3]
	v_mfma_f32_16x16x32_bf16 v[8:11], v[184:187], v[208:211], v[8:11]
	v_mfma_f32_16x16x32_bf16 v[24:27], v[184:187], v[200:203], v[24:27]
	v_mfma_f32_16x16x32_bf16 v[40:43], v[184:187], v[192:195], v[40:43]
	s_setprio 0
	s_barrier
	s_add_i32 s70, 0, 0x18000
	v_add_u32_e32 v136, s70, v148
	s_add_i32 s71, 0, 0x1c000
	ds_read_b128 v[154:157], v136
	ds_read_b128 v[158:161], v136 offset:1024
	ds_read_b128 v[162:165], v136 offset:2048
	ds_read_b128 v[166:169], v136 offset:3072
	v_add_u32_e32 v136, s71, v148
	ds_read_b128 v[172:175], v136
	ds_read_b128 v[176:179], v136 offset:1024
	ds_read_b128 v[180:183], v136 offset:2048
	ds_read_b128 v[184:187], v136 offset:3072
	s_add_u32 s42, s42, 0x40000
	s_addc_u32 s43, s43, 0
	s_mov_b32 m0, s49
	v_lshl_add_u64 v[228:229], s[42:43], 0, v[128:129]
	ds_read_b128 v[188:191], v152 offset:32768
	ds_read_b128 v[192:195], v152 offset:33792
	ds_read_b128 v[196:199], v152 offset:34816
	ds_read_b128 v[200:203], v152 offset:35840
	ds_read_b128 v[204:207], v152 offset:36864
	ds_read_b128 v[208:211], v152 offset:37888
	ds_read_b128 v[212:215], v152 offset:38912
	ds_read_b128 v[216:219], v152 offset:39936
	global_load_lds_dwordx4 v[228:229], off
	v_lshl_add_u64 v[228:229], s[42:43], 0, v[132:133]
	s_mov_b32 m0, s50
	s_nop 0
	global_load_lds_dwordx4 v[228:229], off
	s_waitcnt vmcnt(8)
	s_waitcnt lgkmcnt(0)
	s_barrier
	s_setprio 1
	s_waitcnt lgkmcnt(0)
	v_mfma_f32_16x16x32_bf16 v[124:127], v[154:157], v[188:191], v[124:127]
	v_mfma_f32_16x16x32_bf16 v[116:119], v[154:157], v[196:199], v[116:119]
	v_mfma_f32_16x16x32_bf16 v[108:111], v[154:157], v[204:207], v[108:111]
	v_mfma_f32_16x16x32_bf16 v[76:79], v[154:157], v[212:215], v[76:79]
	v_mfma_f32_16x16x32_bf16 v[72:75], v[162:165], v[212:215], v[72:75]
	v_mfma_f32_16x16x32_bf16 v[100:103], v[162:165], v[204:207], v[100:103]
	v_mfma_f32_16x16x32_bf16 v[112:115], v[162:165], v[196:199], v[112:115]
	v_mfma_f32_16x16x32_bf16 v[120:123], v[162:165], v[188:191], v[120:123]
	v_mfma_f32_16x16x32_bf16 v[124:127], v[158:161], v[192:195], v[124:127]
	v_mfma_f32_16x16x32_bf16 v[116:119], v[158:161], v[200:203], v[116:119]
	v_mfma_f32_16x16x32_bf16 v[108:111], v[158:161], v[208:211], v[108:111]
	v_mfma_f32_16x16x32_bf16 v[76:79], v[158:161], v[216:219], v[76:79]
	v_mfma_f32_16x16x32_bf16 v[72:75], v[166:169], v[216:219], v[72:75]
	v_mfma_f32_16x16x32_bf16 v[100:103], v[166:169], v[208:211], v[100:103]
	v_mfma_f32_16x16x32_bf16 v[112:115], v[166:169], v[200:203], v[112:115]
	v_mfma_f32_16x16x32_bf16 v[120:123], v[166:169], v[192:195], v[120:123]
	s_setprio 0
	s_setprio 1
	v_mfma_f32_16x16x32_bf16 v[104:107], v[172:175], v[188:191], v[104:107]
	v_mfma_f32_16x16x32_bf16 v[92:95], v[172:175], v[196:199], v[92:95]
	v_mfma_f32_16x16x32_bf16 v[84:87], v[172:175], v[204:207], v[84:87]
	v_mfma_f32_16x16x32_bf16 v[68:71], v[172:175], v[212:215], v[68:71]
	v_mfma_f32_16x16x32_bf16 v[64:67], v[180:183], v[212:215], v[64:67]
	v_mfma_f32_16x16x32_bf16 v[80:83], v[180:183], v[204:207], v[80:83]
	v_mfma_f32_16x16x32_bf16 v[88:91], v[180:183], v[196:199], v[88:91]
	v_mfma_f32_16x16x32_bf16 v[96:99], v[180:183], v[188:191], v[96:99]
	v_mfma_f32_16x16x32_bf16 v[104:107], v[176:179], v[192:195], v[104:107]
	v_mfma_f32_16x16x32_bf16 v[92:95], v[176:179], v[200:203], v[92:95]
	v_mfma_f32_16x16x32_bf16 v[84:87], v[176:179], v[208:211], v[84:87]
	v_mfma_f32_16x16x32_bf16 v[68:71], v[176:179], v[216:219], v[68:71]
	v_mfma_f32_16x16x32_bf16 v[64:67], v[184:187], v[216:219], v[64:67]
	v_mfma_f32_16x16x32_bf16 v[80:83], v[184:187], v[208:211], v[80:83]
	v_mfma_f32_16x16x32_bf16 v[88:91], v[184:187], v[200:203], v[88:91]
	v_mfma_f32_16x16x32_bf16 v[96:99], v[184:187], v[192:195], v[96:99]
	s_setprio 0
	s_barrier
	s_add_i32 s42, s70, s46
	v_lshl_add_u64 v[220:221], v[220:221], 0, s[12:13]
	s_mov_b32 m0, s42
	ds_read_b128 v[188:191], v152 offset:49152
	ds_read_b128 v[192:195], v152 offset:50176
	ds_read_b128 v[196:199], v152 offset:51200
	ds_read_b128 v[200:203], v152 offset:52224
	ds_read_b128 v[204:207], v152 offset:53248
	ds_read_b128 v[208:211], v152 offset:54272
	ds_read_b128 v[212:215], v152 offset:55296
	ds_read_b128 v[216:219], v152 offset:56320
	global_load_lds_dwordx4 v[220:221], off
	s_add_i32 m0, s42, 0x2000
	s_add_u32 s40, s40, 0x40080
	v_lshl_add_u64 v[220:221], v[222:223], 0, s[12:13]
	s_addc_u32 s41, s41, 0
	s_add_i32 s42, s71, s46
	global_load_lds_dwordx4 v[220:221], off
	v_lshl_add_u64 v[220:221], s[40:41], 0, v[130:131]
	s_mov_b32 m0, s42
	s_nop 0
	global_load_lds_dwordx4 v[220:221], off
	v_lshl_add_u64 v[220:221], s[40:41], 0, v[134:135]
	s_add_i32 m0, s42, 0x2000
	s_nop 0
	global_load_lds_dwordx4 v[220:221], off
	v_lshl_add_u64 v[220:221], v[224:225], 0, s[12:13]
	s_mov_b32 m0, s52
	s_nop 0
	global_load_lds_dwordx4 v[220:221], off
	v_lshl_add_u64 v[220:221], v[226:227], 0, s[12:13]
	s_mov_b32 m0, s53
	s_nop 0
	global_load_lds_dwordx4 v[220:221], off
	s_waitcnt vmcnt(8)
	s_waitcnt lgkmcnt(0)
	s_barrier
	s_setprio 1
	s_waitcnt lgkmcnt(0)
	v_mfma_f32_16x16x32_bf16 v[60:63], v[154:157], v[188:191], v[60:63]
	v_mfma_f32_16x16x32_bf16 v[52:55], v[154:157], v[196:199], v[52:55]
	v_mfma_f32_16x16x32_bf16 v[36:39], v[154:157], v[204:207], v[36:39]
	v_mfma_f32_16x16x32_bf16 v[20:23], v[154:157], v[212:215], v[20:23]
	v_mfma_f32_16x16x32_bf16 v[12:15], v[162:165], v[212:215], v[12:15]
	v_mfma_f32_16x16x32_bf16 v[28:31], v[162:165], v[204:207], v[28:31]
	v_mfma_f32_16x16x32_bf16 v[44:47], v[162:165], v[196:199], v[44:47]
	v_mfma_f32_16x16x32_bf16 v[56:59], v[162:165], v[188:191], v[56:59]
	v_mfma_f32_16x16x32_bf16 v[60:63], v[158:161], v[192:195], v[60:63]
	v_mfma_f32_16x16x32_bf16 v[52:55], v[158:161], v[200:203], v[52:55]
	v_mfma_f32_16x16x32_bf16 v[36:39], v[158:161], v[208:211], v[36:39]
	v_mfma_f32_16x16x32_bf16 v[20:23], v[158:161], v[216:219], v[20:23]
	v_mfma_f32_16x16x32_bf16 v[12:15], v[166:169], v[216:219], v[12:15]
	v_mfma_f32_16x16x32_bf16 v[28:31], v[166:169], v[208:211], v[28:31]
	v_mfma_f32_16x16x32_bf16 v[44:47], v[166:169], v[200:203], v[44:47]
	v_mfma_f32_16x16x32_bf16 v[56:59], v[166:169], v[192:195], v[56:59]
	s_setprio 0
	s_setprio 1
	v_mfma_f32_16x16x32_bf16 v[48:51], v[172:175], v[188:191], v[48:51]
	v_mfma_f32_16x16x32_bf16 v[32:35], v[172:175], v[196:199], v[32:35]
	v_mfma_f32_16x16x32_bf16 v[16:19], v[172:175], v[204:207], v[16:19]
	v_mfma_f32_16x16x32_bf16 v[4:7], v[172:175], v[212:215], v[4:7]
	v_mfma_f32_16x16x32_bf16 v[0:3], v[180:183], v[212:215], v[0:3]
	v_mfma_f32_16x16x32_bf16 v[8:11], v[180:183], v[204:207], v[8:11]
	v_mfma_f32_16x16x32_bf16 v[24:27], v[180:183], v[196:199], v[24:27]
	v_mfma_f32_16x16x32_bf16 v[40:43], v[180:183], v[188:191], v[40:43]
	v_mfma_f32_16x16x32_bf16 v[48:51], v[176:179], v[192:195], v[48:51]
	v_mfma_f32_16x16x32_bf16 v[32:35], v[176:179], v[200:203], v[32:35]
	v_mfma_f32_16x16x32_bf16 v[16:19], v[176:179], v[208:211], v[16:19]
	v_mfma_f32_16x16x32_bf16 v[4:7], v[176:179], v[216:219], v[4:7]
	v_mfma_f32_16x16x32_bf16 v[0:3], v[184:187], v[216:219], v[0:3]
	v_mfma_f32_16x16x32_bf16 v[8:11], v[184:187], v[208:211], v[8:11]
	v_mfma_f32_16x16x32_bf16 v[24:27], v[184:187], v[200:203], v[24:27]
	v_mfma_f32_16x16x32_bf16 v[40:43], v[184:187], v[192:195], v[40:43]
	s_setprio 0
	s_barrier
	s_add_i32 s69, s69, 2
	s_add_u32 s38, s38, 0x100
	s_addc_u32 s39, s39, 0
	s_add_u32 s67, s67, 0x100
	s_addc_u32 s68, s68, 0
	s_cmp_gt_u32 s69, 13
	s_cbranch_scc0 .LBB0_1269
	s_and_b64 vcc, exec, s[14:15]
	s_cbranch_vccz .LBB0_1272
	s_barrier
